# phase 11: cross-lane max only when a lane exceeds its running reference by >8; per-wave-parity specialised band tiles skip fully masked 16-key sub-tiles; single barrier per tile
# speedup vs baseline: 1.0106x; 1.0094x over previous
; #define NA_WRITE(R, buf) do { bf16_t* kd = KtB + (buf) * (64 * 136) + key * 136 + part * 16; bf16_t* vdp = vtB + (buf) * (128 * 72) + vd * 72 + vc4 * 16; \
;         *(u32x4*)kd = R[0]; *(u32x4*)(kd + 8) = R[1]; *(u32x4*)vdp = R[2]; *(u32x4*)(vdp + 8) = R[3]; } while (0)
; __device__ __forceinline__ void phase_na(const Params& p, unsigned char* lds) {
;     ...
;     for (int u = blockIdx.x; u < 1024; u += gridDim.x) {
;         const int r4 = u & 15, h = (u >> 4) & 15, b = u >> 8, r0 = 4 * r4;
;         const int rs_lo = min(max(r0 - 4, 0), 56), rs_hi = min(max(r0 - 1, 0), 56);
;         const int ntile = 4 + (rs_hi + 8 - rs_lo);
;         const int qr = r0 + (w >> 1), qc0 = 32 * (w & 1);
;         const int rsq = min(max(qr - 4, 0), 56);
;         __syncthreads();
;         for (int e = tid; e < 465; e += 512) rbt[e] = p.rel_bias[h * 465 + e] * 1.4426950408889634f;
;         bf16x8 aq[2][4];
; #pragma unroll
;         for (int mt = 0; mt < 2; ++mt) { const bf16_t* qp = QK + (size_t)(b * SEQ + qr * 64 + qc0 + 16 * mt + fr) * NQK + h * 128 + fq * 8;
; #pragma unroll
;             for (int ks = 0; ks < 4; ++ks) aq[mt][ks] = *(const bf16x8*)(qp + ks * 32); }
;         f32x4 Oa[2][8];
; #pragma unroll
;         for (int mt = 0; mt < 2; ++mt)
; #pragma unroll
;             for (int dt = 0; dt < 8; ++dt) Oa[mt][dt] = (f32x4){0.f, 0.f, 0.f, 0.f};
;         float mrow[2] = {-1e30f, -1e30f}, lrow[2] = {0.f, 0.f};
;         u32x4 ra[4];
;     ...
;         { u32x4 rn[4];
;           NA_LOAD(ra, 0); NA_LOAD(rn, 1); NA_WRITE(ra, 0);
;           ra[0] = rn[0]; ra[1] = rn[1]; ra[2] = rn[2]; ra[3] = rn[3]; }
;         __syncthreads();
;         for (int kt = 0; kt < ntile; ++kt) {
;             if (kt + 1 < ntile) { NA_WRITE(ra, (kt + 1) & 1); if (kt + 2 < ntile) NA_LOAD(ra, kt + 2); }
.Lna_unit:
	s_cmp_ge_u32 s13, 0x400
	s_cbranch_scc1 .Lna_done
	s_lshr_b32 s15, s13, 8
	s_and_b32 s0, s13, 7
	s_bfe_u32 s1, s13, 0x50003
	s_lshr_b32 s14, s1, 4
	s_lshl_b32 s0, s0, 1
	s_or_b32 s14, s14, s0
	s_and_b32 s16, s1, 15
	s_lshl_b32 s16, s16, 2
	s_add_i32 s17, s16, -4
	s_max_i32 s17, s17, 0
	s_min_i32 s17, s17, 56
	s_add_i32 s18, s16, -1
	s_max_i32 s18, s18, 0
	s_min_i32 s18, s18, 56
	s_sub_i32 s18, s18, s17
	s_add_i32 s18, s18, 12
	s_add_i32 s19, s16, s11
	s_add_i32 s20, s19, -4
	s_max_i32 s20, s20, 0
	s_min_i32 s20, s20, 56
	s_barrier
	s_movk_i32 s0, 0x1d1
	v_cmp_gt_u32_e32 vcc, s0, v162
	s_and_saveexec_b64 s[2:3], vcc
	s_mul_i32 s0, s14, 0x1d1
	v_add_lshl_u32 v232, s0, v162, 2
	global_load_dword v234, v232, s[84:85]
	s_mov_b64 exec, s[2:3]
	s_mov_b32 s21, 0
	s_lshl_b32 s28, s15, 8
	s_add_i32 s28, s28, 0x4000
	s_lshl_b32 s29, s21, 6
	s_add_i32 s28, s28, s29
	s_add_i32 s29, s21, s17
	s_add_i32 s29, s29, -4
	s_lshl_b32 s29, s29, 6
	s_lshl_b32 s26, s15, 12
	s_add_i32 s29, s29, s26
	s_cmp_lt_u32 s21, 4
	s_cselect_b32 s28, s28, s29
	s_lshl_b32 s26, s28, 13
	s_lshl_b32 s29, s14, 8
	s_add_i32 s26, s26, s29
	s_add_i32 s26, s26, 0x1000
	s_lshl_b32 s27, s28, 1
	s_mul_i32 s29, s14, 0x440000
	s_add_i32 s27, s27, s29
	v_add_u32_e32 v238, s26, v163
	v_add_u32_e32 v239, s27, v165
	global_load_dwordx4 v[128:131], v238, s[4:5]
	global_load_dwordx4 v[132:135], v238, s[4:5] offset:16
	global_load_dwordx4 v[136:139], v239, s[6:7]
	global_load_dwordx4 v[140:143], v239, s[6:7] offset:16
	s_mov_b32 s21, 1
	s_lshl_b32 s28, s15, 8
	s_add_i32 s28, s28, 0x4000
	s_lshl_b32 s29, s21, 6
	s_add_i32 s28, s28, s29
	s_add_i32 s29, s21, s17
	s_add_i32 s29, s29, -4
	s_lshl_b32 s29, s29, 6
	s_lshl_b32 s26, s15, 12
	s_add_i32 s29, s29, s26
	s_cmp_lt_u32 s21, 4
	s_cselect_b32 s28, s28, s29
	s_lshl_b32 s26, s28, 13
	s_lshl_b32 s29, s14, 8
	s_add_i32 s26, s26, s29
	s_add_i32 s26, s26, 0x1000
	s_lshl_b32 s27, s28, 1
	s_mul_i32 s29, s14, 0x440000
	s_add_i32 s27, s27, s29
	v_add_u32_e32 v238, s26, v163
	v_add_u32_e32 v239, s27, v165
	global_load_dwordx4 v[202:205], v238, s[4:5]
	global_load_dwordx4 v[206:209], v238, s[4:5] offset:16
	global_load_dwordx4 v[210:213], v239, s[6:7]
	global_load_dwordx4 v[214:217], v239, s[6:7] offset:16
	s_lshl_b32 s0, s15, 12
	s_lshl_b32 s1, s19, 6
	s_add_i32 s0, s0, s1
	s_add_i32 s0, s0, s12
	v_and_b32_e32 v232, 15, v162
	v_bfe_u32 v233, v162, 4, 2
	v_add_u32_e32 v232, s0, v232
	v_lshlrev_b32_e32 v232, 13, v232
	v_lshl_add_u32 v232, v233, 4, v232
	s_lshl_b32 s1, s14, 8
	v_add_u32_e32 v232, s1, v232
	v_add_u32_e32 v233, 0x20000, v232
	global_load_dwordx4 v[0:3], v232, s[4:5] offset:0
	global_load_dwordx4 v[4:7], v232, s[4:5] offset:64
	global_load_dwordx4 v[8:11], v232, s[4:5] offset:128
	global_load_dwordx4 v[12:15], v232, s[4:5] offset:192
	global_load_dwordx4 v[16:19], v233, s[4:5] offset:0
	global_load_dwordx4 v[20:23], v233, s[4:5] offset:64
	global_load_dwordx4 v[24:27], v233, s[4:5] offset:128
	global_load_dwordx4 v[28:31], v233, s[4:5] offset:192
	s_mov_b32 s21, 2
	s_lshl_b32 s28, s15, 8
	s_add_i32 s28, s28, 0x4000
	s_lshl_b32 s29, s21, 6
	s_add_i32 s28, s28, s29
	s_add_i32 s29, s21, s17
	s_add_i32 s29, s29, -4
	s_lshl_b32 s29, s29, 6
	s_lshl_b32 s26, s15, 12
	s_add_i32 s29, s29, s26
	s_cmp_lt_u32 s21, 4
	s_cselect_b32 s28, s28, s29
	s_lshl_b32 s26, s28, 13
	s_lshl_b32 s29, s14, 8
	s_add_i32 s26, s26, s29
	s_add_i32 s26, s26, 0x1000
	s_lshl_b32 s27, s28, 1
	s_mul_i32 s29, s14, 0x440000
	s_add_i32 s27, s27, s29
	v_add_u32_e32 v238, s26, v163
	v_add_u32_e32 v239, s27, v165
	global_load_dwordx4 v[170:173], v238, s[4:5]
	global_load_dwordx4 v[174:177], v238, s[4:5] offset:16
	global_load_dwordx4 v[178:181], v239, s[6:7]
	global_load_dwordx4 v[182:185], v239, s[6:7] offset:16
	v_mov_b32_e32 v32, 0
	v_mov_b32_e32 v33, 0
	v_mov_b32_e32 v34, 0
	v_mov_b32_e32 v35, 0
	v_mov_b32_e32 v36, 0
	v_mov_b32_e32 v37, 0
	v_mov_b32_e32 v38, 0
	v_mov_b32_e32 v39, 0
	v_mov_b32_e32 v40, 0
	v_mov_b32_e32 v41, 0
	v_mov_b32_e32 v42, 0
	v_mov_b32_e32 v43, 0
	v_mov_b32_e32 v44, 0
	v_mov_b32_e32 v45, 0
	v_mov_b32_e32 v46, 0
	v_mov_b32_e32 v47, 0
	v_mov_b32_e32 v48, 0
	v_mov_b32_e32 v49, 0
	v_mov_b32_e32 v50, 0
	v_mov_b32_e32 v51, 0
	v_mov_b32_e32 v52, 0
	v_mov_b32_e32 v53, 0
	v_mov_b32_e32 v54, 0
	v_mov_b32_e32 v55, 0
	v_mov_b32_e32 v56, 0
	v_mov_b32_e32 v57, 0
	v_mov_b32_e32 v58, 0
	v_mov_b32_e32 v59, 0
	v_mov_b32_e32 v60, 0
	v_mov_b32_e32 v61, 0
	v_mov_b32_e32 v62, 0
	v_mov_b32_e32 v63, 0
	v_mov_b32_e32 v64, 0
	v_mov_b32_e32 v65, 0
	v_mov_b32_e32 v66, 0
	v_mov_b32_e32 v67, 0
	v_mov_b32_e32 v68, 0
	v_mov_b32_e32 v69, 0
	v_mov_b32_e32 v70, 0
	v_mov_b32_e32 v71, 0
	v_mov_b32_e32 v72, 0
	v_mov_b32_e32 v73, 0
	v_mov_b32_e32 v74, 0
	v_mov_b32_e32 v75, 0
	v_mov_b32_e32 v76, 0
	v_mov_b32_e32 v77, 0
	v_mov_b32_e32 v78, 0
	v_mov_b32_e32 v79, 0
	v_mov_b32_e32 v80, 0
	v_mov_b32_e32 v81, 0
	v_mov_b32_e32 v82, 0
	v_mov_b32_e32 v83, 0
	v_mov_b32_e32 v84, 0
	v_mov_b32_e32 v85, 0
	v_mov_b32_e32 v86, 0
	v_mov_b32_e32 v87, 0
	v_mov_b32_e32 v88, 0
	v_mov_b32_e32 v89, 0
	v_mov_b32_e32 v90, 0
	v_mov_b32_e32 v91, 0
	v_mov_b32_e32 v92, 0
	v_mov_b32_e32 v93, 0
	v_mov_b32_e32 v94, 0
	v_mov_b32_e32 v95, 0
	v_mov_b32_e32 v222, 0xf149f2ca
	v_mov_b32_e32 v224, 0
	v_mov_b32_e32 v226, 0x7149f2ca
	v_mov_b32_e32 v223, 0xf149f2ca
	v_mov_b32_e32 v225, 0
	v_mov_b32_e32 v227, 0x7149f2ca
	s_movk_i32 s0, 0x1d1
	v_cmp_gt_u32_e32 vcc, s0, v162
	v_lshlrev_b32_e32 v235, 2, v162
	v_add_u32_e32 v235, 110848, v235
	s_waitcnt vmcnt(20)
	s_and_saveexec_b64 s[2:3], vcc
	v_mul_f32_e32 v234, 0x413504f3, v234
	ds_write_b32 v235, v234
	s_mov_b64 exec, s[2:3]
	s_waitcnt vmcnt(16)
	ds_write_b128 v164, v[128:131]
	ds_write_b128 v164, v[132:135] offset:16
	ds_write_b128 v166, v[136:139]
	ds_write_b128 v166, v[140:143] offset:16
	s_waitcnt lgkmcnt(0)
	s_barrier
	s_mov_b32 s21, 0
	s_mov_b32 s65, 0
	s_mov_b32 s66, 1
.Lna_tile:
	s_add_i32 s22, s21, 1
	s_cmp_ge_u32 s22, s18
	s_cbranch_scc1 .Lna_noload
	s_mul_i32 s24, s66, 18432
	s_mul_i32 s23, s66, 17408
	v_add_u32_e32 v236, s23, v164
	v_add_u32_e32 v237, s24, v166
	s_add_i32 s23, s21, 2
	s_cmp_ge_u32 s23, s18
	s_cbranch_scc1 .Lna_w0
	s_waitcnt vmcnt(4)
	s_branch .Lna_w1

; __device__ __forceinline__ void phase_na(const Params& p, unsigned char* lds) {
;     ...
;             const bool band = kt >= 4; const int kr = rs_lo + kt - 4;
;             if (!(band && (kr < rsq || kr >= rsq + 8))) {
;                 const bf16_t* Kt = KtB + (kt & 1) * (64 * 136); const bf16_t* vt = vtB + (kt & 1) * (128 * 72);
;                 f32x4 st[2][4];
;                 const int wlo0 = min(max(qc0 - 8, 0), 48), whi0 = min(max(qc0 + 7, 0), 48) + 16, wlo1 = min(max(qc0 + 8, 0), 48), whi1 = min(max(qc0 + 23, 0), 48) + 16;
; #pragma unroll
;                 for (int nt = 0; nt < 4; ++nt) {
;                     const bool act0 = !band || (16 * nt < whi0 && 16 * nt + 16 > wlo0), act1 = !band || (16 * nt < whi1 && 16 * nt + 16 > wlo1);
;                     st[0][nt] = (f32x4){0.f, 0.f, 0.f, 0.f}; st[1][nt] = (f32x4){0.f, 0.f, 0.f, 0.f};
;                     if (act0 || act1) {
;                         bf16x8 Bk[4];
; #pragma unroll
;                         for (int ks = 0; ks < 4; ++ks) Bk[ks] = *(const bf16x8*)(Kt + (nt * 16 + fr) * 136 + ks * 32 + fq * 8);
; #pragma unroll
;                         for (int ks = 0; ks < 4; ++ks) {
;                             if (act0) st[0][nt] = __builtin_amdgcn_mfma_f32_16x16x32_bf16(Bk[ks], aq[0][ks], st[0][nt], 0, 0, 0);
;                             if (act1) st[1][nt] = __builtin_amdgcn_mfma_f32_16x16x32_bf16(Bk[ks], aq[1][ks], st[1][nt], 0, 0, 0); }
;                     }
;                 }
;                 unsigned pk[2][4][2];
; #pragma unroll
;                 for (int mt = 0; mt < 2; ++mt) {
;                     __builtin_amdgcn_sched_barrier(0);
;                     const int c = qc0 + 16 * mt + fr; const int cs = min(max(c - 8, 0), 48); const int wlo = mt ? wlo1 : wlo0, whi = mt ? whi1 : whi0;
;                     float mx = -1e30f;
; #pragma unroll
;                     for (int nt = 0; nt < 4; ++nt) {
;                         const bool act = !band || (16 * nt < whi && 16 * nt + 16 > wlo);
;                         if (act) {
; #pragma unroll
;                             for (int j = 0; j < 4; ++j) { float v = st[mt][nt][j] * scale;
;                                 if (band) { const int kc = nt * 16 + fq * 4 + j; const bool valid = kc >= cs && kc < cs + 16; const int dci = min(max(kc - c + 15, 0), 30);
.Lna_noload:
	s_mul_i32 s24, s65, 18432
	s_mul_i32 s23, s65, 17408
	v_add_u32_e32 v228, s23, v167
	v_add_u32_e32 v229, s24, v168
	s_add_i32 s25, s17, s21
	s_add_i32 s25, s25, -4
	s_sub_i32 s22, s25, s20
	s_cmp_lt_u32 s21, 4
	s_cbranch_scc1 .Lna_c_ctx
	s_cmp_lt_u32 s22, 8
	s_cbranch_scc0 .Lna_tile_end
	s_sub_i32 s22, s25, s19
	s_add_i32 s22, s22, 7
	s_mul_i32 s22, s22, 0x7c
	s_bitcmp1_b32 s10, 0
	s_cbranch_scc1 .Lna_c_band1
.Lna_c_band0:
	v_add_u32_e32 v230, s22, v220
	v_add_u32_e32 v231, s22, v221
	ds_read2_b32 v[96:97], v230 offset0:0 offset1:1
	ds_read2_b32 v[98:99], v230 offset0:2 offset1:3
	ds_read2_b32 v[100:101], v230 offset0:16 offset1:17
	ds_read2_b32 v[102:103], v230 offset0:18 offset1:19
	ds_read2_b32 v[112:113], v231 offset0:0 offset1:1
	ds_read2_b32 v[114:115], v231 offset0:2 offset1:3
	ds_read2_b32 v[116:117], v231 offset0:16 offset1:17
	ds_read2_b32 v[118:119], v231 offset0:18 offset1:19
	ds_read2_b32 v[120:121], v231 offset0:32 offset1:33
	ds_read2_b32 v[122:123], v231 offset0:34 offset1:35
	ds_read_b128 v[128:131], v228 offset:0
	ds_read_b128 v[132:135], v228 offset:64
	ds_read_b128 v[136:139], v228 offset:128
	ds_read_b128 v[140:143], v228 offset:192
	s_waitcnt lgkmcnt(4)
	v_mov_b32_e32 v232, 0xf149f2ca
	v_add_f32_e32 v96, v96, v186
	v_add_f32_e32 v97, v97, v187
	v_add_f32_e32 v98, v98, v188
	v_add_f32_e32 v99, v99, v189
	v_add_f32_e32 v100, v100, v190
	v_add_f32_e32 v101, v101, v191
	v_add_f32_e32 v102, v102, v192
	v_add_f32_e32 v103, v103, v193
	v_cndmask_b32_e64 v112, v232, v112, s[32:33]
	v_cndmask_b32_e64 v113, v232, v113, s[34:35]
	v_cndmask_b32_e64 v114, v232, v114, s[36:37]
	v_cndmask_b32_e64 v115, v232, v115, s[38:39]
	v_cndmask_b32_e64 v116, v232, v116, s[40:41]
	v_cndmask_b32_e64 v117, v232, v117, s[42:43]
	v_cndmask_b32_e64 v118, v232, v118, s[44:45]
	v_cndmask_b32_e64 v119, v232, v119, s[46:47]
	v_cndmask_b32_e64 v120, v232, v120, s[48:49]
	v_cndmask_b32_e64 v121, v232, v121, s[50:51]
	v_cndmask_b32_e64 v122, v232, v122, s[52:53]
	v_cndmask_b32_e64 v123, v232, v123, s[54:55]
	ds_read_b128 v[144:147], v228 offset:4352
	ds_read_b128 v[148:151], v228 offset:4416
	ds_read_b128 v[152:155], v228 offset:4480
	ds_read_b128 v[156:159], v228 offset:4544
	s_waitcnt lgkmcnt(4)
	v_mfma_f32_16x16x32_bf16 v[96:99], v[128:131], v[0:3], v[96:99]
	v_mfma_f32_16x16x32_bf16 v[112:115], v[128:131], v[16:19], v[112:115]
	v_mfma_f32_16x16x32_bf16 v[96:99], v[132:135], v[4:7], v[96:99]
	v_mfma_f32_16x16x32_bf16 v[112:115], v[132:135], v[20:23], v[112:115]
	v_mfma_f32_16x16x32_bf16 v[96:99], v[136:139], v[8:11], v[96:99]
	v_mfma_f32_16x16x32_bf16 v[112:115], v[136:139], v[24:27], v[112:115]
	v_mfma_f32_16x16x32_bf16 v[96:99], v[140:143], v[12:15], v[96:99]
	v_mfma_f32_16x16x32_bf16 v[112:115], v[140:143], v[28:31], v[112:115]
	ds_read_b128 v[128:131], v228 offset:8704
	ds_read_b128 v[132:135], v228 offset:8768
	ds_read_b128 v[136:139], v228 offset:8832
	ds_read_b128 v[140:143], v228 offset:8896
	s_waitcnt lgkmcnt(4)
	v_mfma_f32_16x16x32_bf16 v[100:103], v[144:147], v[0:3], v[100:103]
	v_mfma_f32_16x16x32_bf16 v[116:119], v[144:147], v[16:19], v[116:119]
	v_mfma_f32_16x16x32_bf16 v[100:103], v[148:151], v[4:7], v[100:103]
	v_mfma_f32_16x16x32_bf16 v[116:119], v[148:151], v[20:23], v[116:119]
	v_mfma_f32_16x16x32_bf16 v[100:103], v[152:155], v[8:11], v[100:103]
	v_mfma_f32_16x16x32_bf16 v[116:119], v[152:155], v[24:27], v[116:119]
	v_mfma_f32_16x16x32_bf16 v[100:103], v[156:159], v[12:15], v[100:103]
	v_mfma_f32_16x16x32_bf16 v[116:119], v[156:159], v[28:31], v[116:119]
	s_waitcnt lgkmcnt(0)
	v_mfma_f32_16x16x32_bf16 v[120:123], v[128:131], v[16:19], v[120:123]
	v_mfma_f32_16x16x32_bf16 v[120:123], v[132:135], v[20:23], v[120:123]
	v_mfma_f32_16x16x32_bf16 v[120:123], v[136:139], v[24:27], v[120:123]
	v_mfma_f32_16x16x32_bf16 v[120:123], v[140:143], v[28:31], v[120:123]
	ds_read_b64 v[128:129], v229 offset:0
	ds_read_b64 v[130:131], v229 offset:32
	ds_read_b64 v[132:133], v229 offset:2304
	ds_read_b64 v[134:135], v229 offset:2336
	ds_read_b64 v[136:137], v229 offset:4608
	ds_read_b64 v[138:139], v229 offset:4640
	ds_read_b64 v[140:141], v229 offset:6912
	ds_read_b64 v[142:143], v229 offset:6944
	ds_read_b64 v[144:145], v229 offset:9216
	ds_read_b64 v[146:147], v229 offset:9248
	ds_read_b64 v[148:149], v229 offset:11520
	ds_read_b64 v[150:151], v229 offset:11552
	ds_read_b64 v[152:153], v229 offset:13824
	ds_read_b64 v[154:155], v229 offset:13856
	ds_read_b64 v[156:157], v229 offset:16128
	ds_read_b64 v[158:159], v229 offset:16160
	v_max3_f32 v232, v96, v97, v98
	v_max3_f32 v234, v99, v100, v101
	v_max_f32_e32 v236, v102, v103
	v_max3_f32 v232, v232, v234, v236
	v_max3_f32 v233, v112, v113, v114
	v_max3_f32 v235, v115, v116, v117
	v_max3_f32 v237, v118, v119, v120
	v_max3_f32 v233, v233, v121, v122
	v_max_f32_e32 v233, v233, v123
	v_max3_f32 v233, v233, v235, v237
	v_mul_f32_e32 v232, s30, v232
	v_mul_f32_e32 v233, s30, v233
	v_sub_f32_e32 v236, v232, v222
	v_sub_f32_e32 v237, v233, v223
	v_max_f32_e32 v236, v236, v237
	v_cmp_lt_f32_e32 vcc, 0x41000000, v236
	s_cbranch_vccz .Lna_fast_band0
; __device__ __forceinline__ unsigned pk2(float lo, float hi) { return __builtin_bit_cast(unsigned, __builtin_convertvector((f32x2){lo, hi}, hwbf16x2)); }
; __device__ __forceinline__ void phase_na(const Params& p, unsigned char* lds) {
;     ...
;                     mx = fmaxf(mx, __shfl_xor(mx, 16)); mx = fmaxf(mx, __shfl_xor(mx, 32));
;                     const bool resc = !__all(mx - mrow[mt] <= 8.0f);
;                     float mn = mrow[mt], alpha = 1.f;
;                     if (resc) { mn = fmaxf(mrow[mt], mx); alpha = __builtin_amdgcn_exp2f(mrow[mt] - mn); mrow[mt] = mn; }
;                     float ls = 0.f;
; #pragma unroll
;                     for (int nt = 0; nt < 4; ++nt) {
;                         const bool act = !band || (16 * nt < whi && 16 * nt + 16 > wlo);
;                         if (act) { const float p0 = __builtin_amdgcn_exp2f(st[mt][nt][0] - mn), p1 = __builtin_amdgcn_exp2f(st[mt][nt][1] - mn), p2 = __builtin_amdgcn_exp2f(st[mt][nt][2] - mn), p3 = __builtin_amdgcn_exp2f(st[mt][nt][3] - mn);
;                             ls += (p0 + p1) + (p2 + p3); pk[mt][nt][0] = pk2(p0, p1); pk[mt][nt][1] = pk2(p2, p3); }
;                         else { pk[mt][nt][0] = 0u; pk[mt][nt][1] = 0u; }
;                     }
;                     lrow[mt] = lrow[mt] * alpha + ls;
	ds_bpermute_b32 v234, v218, v232
	ds_bpermute_b32 v235, v218, v233
	s_waitcnt lgkmcnt(0)
	v_max_f32_e32 v232, v232, v234
	v_max_f32_e32 v233, v233, v235
	ds_bpermute_b32 v234, v219, v232
	ds_bpermute_b32 v235, v219, v233
	s_waitcnt lgkmcnt(0)
	v_max_f32_e32 v232, v232, v234
	v_max_f32_e32 v233, v233, v235
	v_max_f32_e32 v236, v222, v232
	v_sub_f32_e32 v237, v222, v236
	v_exp_f32_e32 v237, v237
	v_mov_b32_e32 v222, v236
	v_sub_f32_e32 v226, 0, v236
	v_mul_f32_e32 v224, v224, v237
	v_mul_f32_e32 v32, v32, v237
	v_mul_f32_e32 v33, v33, v237
	v_mul_f32_e32 v34, v34, v237
	v_mul_f32_e32 v35, v35, v237
	v_mul_f32_e32 v36, v36, v237
	v_mul_f32_e32 v37, v37, v237
	v_mul_f32_e32 v38, v38, v237
	v_mul_f32_e32 v39, v39, v237
	v_mul_f32_e32 v40, v40, v237
	v_mul_f32_e32 v41, v41, v237
	v_mul_f32_e32 v42, v42, v237
	v_mul_f32_e32 v43, v43, v237
	v_mul_f32_e32 v44, v44, v237
	v_mul_f32_e32 v45, v45, v237
	v_mul_f32_e32 v46, v46, v237
	v_mul_f32_e32 v47, v47, v237
	v_mul_f32_e32 v48, v48, v237
	v_mul_f32_e32 v49, v49, v237
	v_mul_f32_e32 v50, v50, v237
	v_mul_f32_e32 v51, v51, v237
	v_mul_f32_e32 v52, v52, v237
	v_mul_f32_e32 v53, v53, v237
	v_mul_f32_e32 v54, v54, v237
	v_mul_f32_e32 v55, v55, v237
	v_mul_f32_e32 v56, v56, v237
	v_mul_f32_e32 v57, v57, v237
	v_mul_f32_e32 v58, v58, v237
	v_mul_f32_e32 v59, v59, v237
	v_mul_f32_e32 v60, v60, v237
	v_mul_f32_e32 v61, v61, v237
	v_mul_f32_e32 v62, v62, v237
	v_mul_f32_e32 v63, v63, v237
	v_max_f32_e32 v236, v223, v233
	v_sub_f32_e32 v237, v223, v236
	v_exp_f32_e32 v237, v237
	v_mov_b32_e32 v223, v236
	v_sub_f32_e32 v227, 0, v236
	v_mul_f32_e32 v225, v225, v237
	v_mul_f32_e32 v64, v64, v237
	v_mul_f32_e32 v65, v65, v237
	v_mul_f32_e32 v66, v66, v237
	v_mul_f32_e32 v67, v67, v237
	v_mul_f32_e32 v68, v68, v237
	v_mul_f32_e32 v69, v69, v237
	v_mul_f32_e32 v70, v70, v237
	v_mul_f32_e32 v71, v71, v237
	v_mul_f32_e32 v72, v72, v237
	v_mul_f32_e32 v73, v73, v237
	v_mul_f32_e32 v74, v74, v237
	v_mul_f32_e32 v75, v75, v237
	v_mul_f32_e32 v76, v76, v237
	v_mul_f32_e32 v77, v77, v237
	v_mul_f32_e32 v78, v78, v237
	v_mul_f32_e32 v79, v79, v237
	v_mul_f32_e32 v80, v80, v237
	v_mul_f32_e32 v81, v81, v237
	v_mul_f32_e32 v82, v82, v237
	v_mul_f32_e32 v83, v83, v237
	v_mul_f32_e32 v84, v84, v237
	v_mul_f32_e32 v85, v85, v237
	v_mul_f32_e32 v86, v86, v237
	v_mul_f32_e32 v87, v87, v237
	v_mul_f32_e32 v88, v88, v237
	v_mul_f32_e32 v89, v89, v237
	v_mul_f32_e32 v90, v90, v237
	v_mul_f32_e32 v91, v91, v237
	v_mul_f32_e32 v92, v92, v237
	v_mul_f32_e32 v93, v93, v237
	v_mul_f32_e32 v94, v94, v237
	v_mul_f32_e32 v95, v95, v237
.Lna_fast_band0:
	v_fma_f32 v96, v96, s30, v226
	v_fma_f32 v97, v97, s30, v226
	v_fma_f32 v98, v98, s30, v226
	v_fma_f32 v99, v99, s30, v226
	v_fma_f32 v100, v100, s30, v226
	v_fma_f32 v101, v101, s30, v226
	v_fma_f32 v102, v102, s30, v226
	v_fma_f32 v103, v103, s30, v226
	v_fma_f32 v112, v112, s30, v227
	v_fma_f32 v113, v113, s30, v227
	v_fma_f32 v114, v114, s30, v227
	v_fma_f32 v115, v115, s30, v227
	v_fma_f32 v116, v116, s30, v227
	v_fma_f32 v117, v117, s30, v227
	v_fma_f32 v118, v118, s30, v227
	v_fma_f32 v119, v119, s30, v227
	v_fma_f32 v120, v120, s30, v227
	v_fma_f32 v121, v121, s30, v227
	v_fma_f32 v122, v122, s30, v227
	v_fma_f32 v123, v123, s30, v227
	v_exp_f32_e32 v96, v96
	v_exp_f32_e32 v97, v97
	v_exp_f32_e32 v98, v98
	v_exp_f32_e32 v99, v99
	v_exp_f32_e32 v100, v100
	v_exp_f32_e32 v101, v101
	v_exp_f32_e32 v102, v102
	v_exp_f32_e32 v103, v103
	v_exp_f32_e32 v112, v112
	v_exp_f32_e32 v113, v113
	v_exp_f32_e32 v114, v114
	v_exp_f32_e32 v115, v115
	v_exp_f32_e32 v116, v116
	v_exp_f32_e32 v117, v117
	v_exp_f32_e32 v118, v118
	v_exp_f32_e32 v119, v119
	v_exp_f32_e32 v120, v120
	v_exp_f32_e32 v121, v121
	v_exp_f32_e32 v122, v122
	v_exp_f32_e32 v123, v123
	v_add_f32_e32 v232, v96, v97
	v_add_f32_e32 v232, v232, v98
	v_add_f32_e32 v232, v232, v99
	v_add_f32_e32 v232, v232, v100
	v_add_f32_e32 v232, v232, v101
	v_add_f32_e32 v232, v232, v102
	v_add_f32_e32 v232, v232, v103
	v_add_f32_e32 v224, v224, v232
	v_add_f32_e32 v233, v112, v113
	v_add_f32_e32 v233, v233, v114
	v_add_f32_e32 v233, v233, v115
	v_add_f32_e32 v233, v233, v116
	v_add_f32_e32 v233, v233, v117
	v_add_f32_e32 v233, v233, v118
	v_add_f32_e32 v233, v233, v119
	v_add_f32_e32 v233, v233, v120
	v_add_f32_e32 v233, v233, v121
	v_add_f32_e32 v233, v233, v122
	v_add_f32_e32 v233, v233, v123
	v_add_f32_e32 v225, v225, v233
	v_cvt_pk_bf16_f32 v96, v96, v97
	v_cvt_pk_bf16_f32 v97, v98, v99
	v_cvt_pk_bf16_f32 v98, v100, v101
	v_cvt_pk_bf16_f32 v99, v102, v103
	v_cvt_pk_bf16_f32 v112, v112, v113
	v_cvt_pk_bf16_f32 v113, v114, v115
	v_cvt_pk_bf16_f32 v114, v116, v117
	v_cvt_pk_bf16_f32 v115, v118, v119
	v_cvt_pk_bf16_f32 v120, v120, v121
	v_cvt_pk_bf16_f32 v121, v122, v123
	v_mov_b32_e32 v122, 0
	v_mov_b32_e32 v123, 0
	s_waitcnt lgkmcnt(0)
; __device__ __forceinline__ void phase_na(const Params& p, unsigned char* lds) {
;     ...
;             const bool band = kt >= 4; const int kr = rs_lo + kt - 4;
;             if (!(band && (kr < rsq || kr >= rsq + 8))) {
;                 const bf16_t* Kt = KtB + (kt & 1) * (64 * 136); const bf16_t* vt = vtB + (kt & 1) * (128 * 72);
;                 f32x4 st[2][4];
;                 const int wlo0 = min(max(qc0 - 8, 0), 48), whi0 = min(max(qc0 + 7, 0), 48) + 16, wlo1 = min(max(qc0 + 8, 0), 48), whi1 = min(max(qc0 + 23, 0), 48) + 16;
; #pragma unroll
;                 for (int nt = 0; nt < 4; ++nt) {
;                     const bool act0 = !band || (16 * nt < whi0 && 16 * nt + 16 > wlo0), act1 = !band || (16 * nt < whi1 && 16 * nt + 16 > wlo1);
;                     st[0][nt] = (f32x4){0.f, 0.f, 0.f, 0.f}; st[1][nt] = (f32x4){0.f, 0.f, 0.f, 0.f};
;                     if (act0 || act1) {
;                         bf16x8 Bk[4];
; #pragma unroll
;                         for (int ks = 0; ks < 4; ++ks) Bk[ks] = *(const bf16x8*)(Kt + (nt * 16 + fr) * 136 + ks * 32 + fq * 8);
; #pragma unroll
;     ...
; #pragma unroll
;                 for (int kk = 0; kk < 2; ++kk) {
;                     const int ta = 2 * kk, tb = 2 * kk + 1;
;                     const bf16x8 Bp0 = as_bf16x8((u32x4){pk[0][ta][0], pk[0][ta][1], pk[0][tb][0], pk[0][tb][1]}), Bp1 = as_bf16x8((u32x4){pk[1][ta][0], pk[1][ta][1], pk[1][tb][0], pk[1][tb][1]});
; #pragma unroll
;                     for (int dt = 0; dt < 8; ++dt) {
;                         const u32x2 va = *(const u32x2*)(vt + (dt * 16 + fr) * 72 + 16 * ta + fq * 4), vb = *(const u32x2*)(vt + (dt * 16 + fr) * 72 + 16 * tb + fq * 4);
;                         const bf16x8 Av = as_bf16x8((u32x4){va.x, va.y, vb.x, vb.y});
;                         Oa[0][dt] = __builtin_amdgcn_mfma_f32_16x16x32_bf16(Av, Bp0, Oa[0][dt], 0, 0, 0);
;                         Oa[1][dt] = __builtin_amdgcn_mfma_f32_16x16x32_bf16(Av, Bp1, Oa[1][dt], 0, 0, 0); }
;                     __builtin_amdgcn_sched_group_barrier(0x100, 8, 0);
; #pragma unroll
;                     for (int q = 0; q < 4; ++q) { __builtin_amdgcn_sched_group_barrier(0x008, 2, 0); __builtin_amdgcn_sched_group_barrier(0x100, 2, 0); }
;                     __builtin_amdgcn_sched_group_barrier(0x008, 8, 0);
;                     __builtin_amdgcn_sched_barrier(0);
;                 }
	s_nop 1
	v_mfma_f32_16x16x32_bf16 v[32:35], v[128:131], v[96:99], v[32:35]
	v_mfma_f32_16x16x32_bf16 v[64:67], v[128:131], v[112:115], v[64:67]
	v_mfma_f32_16x16x32_bf16 v[36:39], v[132:135], v[96:99], v[36:39]
	v_mfma_f32_16x16x32_bf16 v[68:71], v[132:135], v[112:115], v[68:71]
	v_mfma_f32_16x16x32_bf16 v[40:43], v[136:139], v[96:99], v[40:43]
	v_mfma_f32_16x16x32_bf16 v[72:75], v[136:139], v[112:115], v[72:75]
	v_mfma_f32_16x16x32_bf16 v[44:47], v[140:143], v[96:99], v[44:47]
	v_mfma_f32_16x16x32_bf16 v[76:79], v[140:143], v[112:115], v[76:79]
	ds_read_b64 v[128:129], v229 offset:64
	ds_read_b64 v[130:131], v229 offset:96
	ds_read_b64 v[132:133], v229 offset:2368
	ds_read_b64 v[134:135], v229 offset:2400
	ds_read_b64 v[136:137], v229 offset:4672
	ds_read_b64 v[138:139], v229 offset:4704
	ds_read_b64 v[140:141], v229 offset:6976
	ds_read_b64 v[142:143], v229 offset:7008
	v_mfma_f32_16x16x32_bf16 v[48:51], v[144:147], v[96:99], v[48:51]
	v_mfma_f32_16x16x32_bf16 v[80:83], v[144:147], v[112:115], v[80:83]
	v_mfma_f32_16x16x32_bf16 v[52:55], v[148:151], v[96:99], v[52:55]
	v_mfma_f32_16x16x32_bf16 v[84:87], v[148:151], v[112:115], v[84:87]
	v_mfma_f32_16x16x32_bf16 v[56:59], v[152:155], v[96:99], v[56:59]
	v_mfma_f32_16x16x32_bf16 v[88:91], v[152:155], v[112:115], v[88:91]
	v_mfma_f32_16x16x32_bf16 v[60:63], v[156:159], v[96:99], v[60:63]
	v_mfma_f32_16x16x32_bf16 v[92:95], v[156:159], v[112:115], v[92:95]
	ds_read_b64 v[144:145], v229 offset:9280
	ds_read_b64 v[146:147], v229 offset:9312
	ds_read_b64 v[148:149], v229 offset:11584
	ds_read_b64 v[150:151], v229 offset:11616
	ds_read_b64 v[152:153], v229 offset:13888
	ds_read_b64 v[154:155], v229 offset:13920
	ds_read_b64 v[156:157], v229 offset:16192
	ds_read_b64 v[158:159], v229 offset:16224
	s_waitcnt lgkmcnt(8)
	v_mfma_f32_16x16x32_bf16 v[64:67], v[128:131], v[120:123], v[64:67]
	v_mfma_f32_16x16x32_bf16 v[68:71], v[132:135], v[120:123], v[68:71]
	v_mfma_f32_16x16x32_bf16 v[72:75], v[136:139], v[120:123], v[72:75]
	v_mfma_f32_16x16x32_bf16 v[76:79], v[140:143], v[120:123], v[76:79]
	s_waitcnt lgkmcnt(0)
	v_mfma_f32_16x16x32_bf16 v[80:83], v[144:147], v[120:123], v[80:83]
	v_mfma_f32_16x16x32_bf16 v[84:87], v[148:151], v[120:123], v[84:87]
	v_mfma_f32_16x16x32_bf16 v[88:91], v[152:155], v[120:123], v[88:91]
	v_mfma_f32_16x16x32_bf16 v[92:95], v[156:159], v[120:123], v[92:95]
	s_branch .Lna_tile_end
.Lna_c_band1:
	v_add_u32_e32 v230, s22, v220
	v_add_u32_e32 v231, s22, v221
	ds_read2_b32 v[100:101], v230 offset0:16 offset1:17
	ds_read2_b32 v[102:103], v230 offset0:18 offset1:19
	ds_read2_b32 v[104:105], v230 offset0:32 offset1:33
	ds_read2_b32 v[106:107], v230 offset0:34 offset1:35
	ds_read2_b32 v[108:109], v230 offset0:48 offset1:49
	ds_read2_b32 v[110:111], v230 offset0:50 offset1:51
	ds_read2_b32 v[120:121], v231 offset0:32 offset1:33
	ds_read2_b32 v[122:123], v231 offset0:34 offset1:35
	ds_read2_b32 v[124:125], v231 offset0:48 offset1:49
	ds_read2_b32 v[126:127], v231 offset0:50 offset1:51
	ds_read_b128 v[128:131], v228 offset:4352
	ds_read_b128 v[132:135], v228 offset:4416
	ds_read_b128 v[136:139], v228 offset:4480
	ds_read_b128 v[140:143], v228 offset:4544
	s_waitcnt lgkmcnt(4)
	v_mov_b32_e32 v232, 0xf149f2ca
	v_add_f32_e32 v100, v100, v190
	v_add_f32_e32 v101, v101, v191
	v_add_f32_e32 v102, v102, v192
	v_add_f32_e32 v103, v103, v193
	v_add_f32_e32 v104, v104, v194
	v_add_f32_e32 v105, v105, v195
	v_add_f32_e32 v106, v106, v196
	v_add_f32_e32 v107, v107, v197
	v_add_f32_e32 v108, v108, v198
	v_add_f32_e32 v109, v109, v199
	v_add_f32_e32 v110, v110, v200
	v_add_f32_e32 v111, v111, v201
	v_cndmask_b32_e64 v120, v232, v120, s[48:49]
	v_cndmask_b32_e64 v121, v232, v121, s[50:51]
	v_cndmask_b32_e64 v122, v232, v122, s[52:53]
	v_cndmask_b32_e64 v123, v232, v123, s[54:55]
	v_cndmask_b32_e64 v124, v232, v124, s[56:57]
	v_cndmask_b32_e64 v125, v232, v125, s[58:59]
	v_cndmask_b32_e64 v126, v232, v126, s[60:61]
	v_cndmask_b32_e64 v127, v232, v127, s[62:63]
	ds_read_b128 v[144:147], v228 offset:8704
	ds_read_b128 v[148:151], v228 offset:8768
	ds_read_b128 v[152:155], v228 offset:8832
	ds_read_b128 v[156:159], v228 offset:8896
	s_waitcnt lgkmcnt(4)
	v_mfma_f32_16x16x32_bf16 v[100:103], v[128:131], v[0:3], v[100:103]
	v_mfma_f32_16x16x32_bf16 v[100:103], v[132:135], v[4:7], v[100:103]
	v_mfma_f32_16x16x32_bf16 v[100:103], v[136:139], v[8:11], v[100:103]
	v_mfma_f32_16x16x32_bf16 v[100:103], v[140:143], v[12:15], v[100:103]
	ds_read_b128 v[128:131], v228 offset:13056
	ds_read_b128 v[132:135], v228 offset:13120
	ds_read_b128 v[136:139], v228 offset:13184
	ds_read_b128 v[140:143], v228 offset:13248
	s_waitcnt lgkmcnt(4)
	v_mfma_f32_16x16x32_bf16 v[104:107], v[144:147], v[0:3], v[104:107]
	v_mfma_f32_16x16x32_bf16 v[120:123], v[144:147], v[16:19], v[120:123]
	v_mfma_f32_16x16x32_bf16 v[104:107], v[148:151], v[4:7], v[104:107]
	v_mfma_f32_16x16x32_bf16 v[120:123], v[148:151], v[20:23], v[120:123]
	v_mfma_f32_16x16x32_bf16 v[104:107], v[152:155], v[8:11], v[104:107]
	v_mfma_f32_16x16x32_bf16 v[120:123], v[152:155], v[24:27], v[120:123]
	v_mfma_f32_16x16x32_bf16 v[104:107], v[156:159], v[12:15], v[104:107]
	v_mfma_f32_16x16x32_bf16 v[120:123], v[156:159], v[28:31], v[120:123]
	s_waitcnt lgkmcnt(0)
	v_mfma_f32_16x16x32_bf16 v[108:111], v[128:131], v[0:3], v[108:111]
	v_mfma_f32_16x16x32_bf16 v[124:127], v[128:131], v[16:19], v[124:127]
	v_mfma_f32_16x16x32_bf16 v[108:111], v[132:135], v[4:7], v[108:111]
	v_mfma_f32_16x16x32_bf16 v[124:127], v[132:135], v[20:23], v[124:127]
	v_mfma_f32_16x16x32_bf16 v[108:111], v[136:139], v[8:11], v[108:111]
	v_mfma_f32_16x16x32_bf16 v[124:127], v[136:139], v[24:27], v[124:127]
	v_mfma_f32_16x16x32_bf16 v[108:111], v[140:143], v[12:15], v[108:111]
	v_mfma_f32_16x16x32_bf16 v[124:127], v[140:143], v[28:31], v[124:127]
	ds_read_b64 v[128:129], v229 offset:0
	ds_read_b64 v[130:131], v229 offset:32
	ds_read_b64 v[132:133], v229 offset:2304
	ds_read_b64 v[134:135], v229 offset:2336
	ds_read_b64 v[136:137], v229 offset:4608
	ds_read_b64 v[138:139], v229 offset:4640
	ds_read_b64 v[140:141], v229 offset:6912
	ds_read_b64 v[142:143], v229 offset:6944
	ds_read_b64 v[144:145], v229 offset:9216
	ds_read_b64 v[146:147], v229 offset:9248
	ds_read_b64 v[148:149], v229 offset:11520
	ds_read_b64 v[150:151], v229 offset:11552
	ds_read_b64 v[152:153], v229 offset:13824
	ds_read_b64 v[154:155], v229 offset:13856
	ds_read_b64 v[156:157], v229 offset:16128
	ds_read_b64 v[158:159], v229 offset:16160
	v_max3_f32 v232, v100, v101, v102
	v_max3_f32 v234, v103, v104, v105
	v_max3_f32 v236, v106, v107, v108
	v_max3_f32 v232, v232, v109, v110
	v_max_f32_e32 v232, v232, v111
	v_max3_f32 v232, v232, v234, v236
	v_max3_f32 v233, v120, v121, v122
	v_max3_f32 v235, v123, v124, v125
	v_max_f32_e32 v237, v126, v127
	v_max3_f32 v233, v233, v235, v237
	v_mul_f32_e32 v232, s30, v232
	v_mul_f32_e32 v233, s30, v233
	v_sub_f32_e32 v236, v232, v222
	v_sub_f32_e32 v237, v233, v223
	v_max_f32_e32 v236, v236, v237
	v_cmp_lt_f32_e32 vcc, 0x41000000, v236
	s_cbranch_vccz .Lna_fast_band1
; __device__ __forceinline__ unsigned pk2(float lo, float hi) { return __builtin_bit_cast(unsigned, __builtin_convertvector((f32x2){lo, hi}, hwbf16x2)); }
; __device__ __forceinline__ void phase_na(const Params& p, unsigned char* lds) {
;     ...
;                     mx = fmaxf(mx, __shfl_xor(mx, 16)); mx = fmaxf(mx, __shfl_xor(mx, 32));
;                     const bool resc = !__all(mx - mrow[mt] <= 8.0f);
;                     float mn = mrow[mt], alpha = 1.f;
;                     if (resc) { mn = fmaxf(mrow[mt], mx); alpha = __builtin_amdgcn_exp2f(mrow[mt] - mn); mrow[mt] = mn; }
;                     float ls = 0.f;
; #pragma unroll
;                     for (int nt = 0; nt < 4; ++nt) {
;                         const bool act = !band || (16 * nt < whi && 16 * nt + 16 > wlo);
;                         if (act) { const float p0 = __builtin_amdgcn_exp2f(st[mt][nt][0] - mn), p1 = __builtin_amdgcn_exp2f(st[mt][nt][1] - mn), p2 = __builtin_amdgcn_exp2f(st[mt][nt][2] - mn), p3 = __builtin_amdgcn_exp2f(st[mt][nt][3] - mn);
;                             ls += (p0 + p1) + (p2 + p3); pk[mt][nt][0] = pk2(p0, p1); pk[mt][nt][1] = pk2(p2, p3); }
;                         else { pk[mt][nt][0] = 0u; pk[mt][nt][1] = 0u; }
;                     }
;                     lrow[mt] = lrow[mt] * alpha + ls;
;                     if (resc) {
; #pragma unroll
;                         for (int dt = 0; dt < 8; ++dt) Oa[mt][dt] = Oa[mt][dt] * alpha; }
;                 }
;                 __builtin_amdgcn_sched_barrier(0);
; #pragma unroll
;                 for (int kk = 0; kk < 2; ++kk) {
;                     const int ta = 2 * kk, tb = 2 * kk + 1;
;                     const bf16x8 Bp0 = as_bf16x8((u32x4){pk[0][ta][0], pk[0][ta][1], pk[0][tb][0], pk[0][tb][1]}), Bp1 = as_bf16x8((u32x4){pk[1][ta][0], pk[1][ta][1], pk[1][tb][0], pk[1][tb][1]});
; #pragma unroll
;                     for (int dt = 0; dt < 8; ++dt) {
;                         const u32x2 va = *(const u32x2*)(vt + (dt * 16 + fr) * 72 + 16 * ta + fq * 4), vb = *(const u32x2*)(vt + (dt * 16 + fr) * 72 + 16 * tb + fq * 4);
;                         const bf16x8 Av = as_bf16x8((u32x4){va.x, va.y, vb.x, vb.y});
;                         Oa[0][dt] = __builtin_amdgcn_mfma_f32_16x16x32_bf16(Av, Bp0, Oa[0][dt], 0, 0, 0);
;                         Oa[1][dt] = __builtin_amdgcn_mfma_f32_16x16x32_bf16(Av, Bp1, Oa[1][dt], 0, 0, 0); }
	ds_bpermute_b32 v234, v218, v232
	ds_bpermute_b32 v235, v218, v233
	s_waitcnt lgkmcnt(0)
	v_max_f32_e32 v232, v232, v234
	v_max_f32_e32 v233, v233, v235
	ds_bpermute_b32 v234, v219, v232
	ds_bpermute_b32 v235, v219, v233
	s_waitcnt lgkmcnt(0)
	v_max_f32_e32 v232, v232, v234
	v_max_f32_e32 v233, v233, v235
	v_max_f32_e32 v236, v222, v232
	v_sub_f32_e32 v237, v222, v236
	v_exp_f32_e32 v237, v237
	v_mov_b32_e32 v222, v236
	v_sub_f32_e32 v226, 0, v236
	v_mul_f32_e32 v224, v224, v237
	v_mul_f32_e32 v32, v32, v237
	v_mul_f32_e32 v33, v33, v237
	v_mul_f32_e32 v34, v34, v237
	v_mul_f32_e32 v35, v35, v237
	v_mul_f32_e32 v36, v36, v237
	v_mul_f32_e32 v37, v37, v237
	v_mul_f32_e32 v38, v38, v237
	v_mul_f32_e32 v39, v39, v237
	v_mul_f32_e32 v40, v40, v237
	v_mul_f32_e32 v41, v41, v237
	v_mul_f32_e32 v42, v42, v237
	v_mul_f32_e32 v43, v43, v237
	v_mul_f32_e32 v44, v44, v237
	v_mul_f32_e32 v45, v45, v237
	v_mul_f32_e32 v46, v46, v237
	v_mul_f32_e32 v47, v47, v237
	v_mul_f32_e32 v48, v48, v237
	v_mul_f32_e32 v49, v49, v237
	v_mul_f32_e32 v50, v50, v237
	v_mul_f32_e32 v51, v51, v237
	v_mul_f32_e32 v52, v52, v237
	v_mul_f32_e32 v53, v53, v237
	v_mul_f32_e32 v54, v54, v237
	v_mul_f32_e32 v55, v55, v237
	v_mul_f32_e32 v56, v56, v237
	v_mul_f32_e32 v57, v57, v237
	v_mul_f32_e32 v58, v58, v237
	v_mul_f32_e32 v59, v59, v237
	v_mul_f32_e32 v60, v60, v237
	v_mul_f32_e32 v61, v61, v237
	v_mul_f32_e32 v62, v62, v237
	v_mul_f32_e32 v63, v63, v237
	v_max_f32_e32 v236, v223, v233
	v_sub_f32_e32 v237, v223, v236
	v_exp_f32_e32 v237, v237
	v_mov_b32_e32 v223, v236
	v_sub_f32_e32 v227, 0, v236
	v_mul_f32_e32 v225, v225, v237
	v_mul_f32_e32 v64, v64, v237
	v_mul_f32_e32 v65, v65, v237
	v_mul_f32_e32 v66, v66, v237
	v_mul_f32_e32 v67, v67, v237
	v_mul_f32_e32 v68, v68, v237
	v_mul_f32_e32 v69, v69, v237
	v_mul_f32_e32 v70, v70, v237
	v_mul_f32_e32 v71, v71, v237
	v_mul_f32_e32 v72, v72, v237
	v_mul_f32_e32 v73, v73, v237
	v_mul_f32_e32 v74, v74, v237
	v_mul_f32_e32 v75, v75, v237
	v_mul_f32_e32 v76, v76, v237
	v_mul_f32_e32 v77, v77, v237
	v_mul_f32_e32 v78, v78, v237
	v_mul_f32_e32 v79, v79, v237
	v_mul_f32_e32 v80, v80, v237
	v_mul_f32_e32 v81, v81, v237
	v_mul_f32_e32 v82, v82, v237
	v_mul_f32_e32 v83, v83, v237
	v_mul_f32_e32 v84, v84, v237
	v_mul_f32_e32 v85, v85, v237
	v_mul_f32_e32 v86, v86, v237
	v_mul_f32_e32 v87, v87, v237
	v_mul_f32_e32 v88, v88, v237
	v_mul_f32_e32 v89, v89, v237
	v_mul_f32_e32 v90, v90, v237
	v_mul_f32_e32 v91, v91, v237
	v_mul_f32_e32 v92, v92, v237
	v_mul_f32_e32 v93, v93, v237
	v_mul_f32_e32 v94, v94, v237
	v_mul_f32_e32 v95, v95, v237
.Lna_fast_band1:
	v_fma_f32 v100, v100, s30, v226
	v_fma_f32 v101, v101, s30, v226
	v_fma_f32 v102, v102, s30, v226
	v_fma_f32 v103, v103, s30, v226
	v_fma_f32 v104, v104, s30, v226
	v_fma_f32 v105, v105, s30, v226
	v_fma_f32 v106, v106, s30, v226
	v_fma_f32 v107, v107, s30, v226
	v_fma_f32 v108, v108, s30, v226
	v_fma_f32 v109, v109, s30, v226
	v_fma_f32 v110, v110, s30, v226
	v_fma_f32 v111, v111, s30, v226
	v_fma_f32 v120, v120, s30, v227
	v_fma_f32 v121, v121, s30, v227
	v_fma_f32 v122, v122, s30, v227
	v_fma_f32 v123, v123, s30, v227
	v_fma_f32 v124, v124, s30, v227
	v_fma_f32 v125, v125, s30, v227
	v_fma_f32 v126, v126, s30, v227
	v_fma_f32 v127, v127, s30, v227
	v_exp_f32_e32 v100, v100
	v_exp_f32_e32 v101, v101
	v_exp_f32_e32 v102, v102
	v_exp_f32_e32 v103, v103
	v_exp_f32_e32 v104, v104
	v_exp_f32_e32 v105, v105
	v_exp_f32_e32 v106, v106
	v_exp_f32_e32 v107, v107
	v_exp_f32_e32 v108, v108
	v_exp_f32_e32 v109, v109
	v_exp_f32_e32 v110, v110
	v_exp_f32_e32 v111, v111
	v_exp_f32_e32 v120, v120
	v_exp_f32_e32 v121, v121
	v_exp_f32_e32 v122, v122
	v_exp_f32_e32 v123, v123
	v_exp_f32_e32 v124, v124
	v_exp_f32_e32 v125, v125
	v_exp_f32_e32 v126, v126
	v_exp_f32_e32 v127, v127
	v_add_f32_e32 v232, v100, v101
	v_add_f32_e32 v232, v232, v102
	v_add_f32_e32 v232, v232, v103
	v_add_f32_e32 v232, v232, v104
	v_add_f32_e32 v232, v232, v105
	v_add_f32_e32 v232, v232, v106
	v_add_f32_e32 v232, v232, v107
	v_add_f32_e32 v232, v232, v108
	v_add_f32_e32 v232, v232, v109
	v_add_f32_e32 v232, v232, v110
	v_add_f32_e32 v232, v232, v111
	v_add_f32_e32 v224, v224, v232
	v_add_f32_e32 v233, v120, v121
	v_add_f32_e32 v233, v233, v122
	v_add_f32_e32 v233, v233, v123
	v_add_f32_e32 v233, v233, v124
	v_add_f32_e32 v233, v233, v125
	v_add_f32_e32 v233, v233, v126
	v_add_f32_e32 v233, v233, v127
	v_add_f32_e32 v225, v225, v233
	v_mov_b32_e32 v96, 0
	v_mov_b32_e32 v97, 0
	v_cvt_pk_bf16_f32 v98, v100, v101
	v_cvt_pk_bf16_f32 v99, v102, v103
	v_cvt_pk_bf16_f32 v104, v104, v105
	v_cvt_pk_bf16_f32 v105, v106, v107
	v_cvt_pk_bf16_f32 v106, v108, v109
	v_cvt_pk_bf16_f32 v107, v110, v111
	v_cvt_pk_bf16_f32 v120, v120, v121
	v_cvt_pk_bf16_f32 v121, v122, v123
	v_cvt_pk_bf16_f32 v122, v124, v125
	v_cvt_pk_bf16_f32 v123, v126, v127
	s_waitcnt lgkmcnt(0)
	s_nop 1
	v_mfma_f32_16x16x32_bf16 v[32:35], v[128:131], v[96:99], v[32:35]
	v_mfma_f32_16x16x32_bf16 v[36:39], v[132:135], v[96:99], v[36:39]
	v_mfma_f32_16x16x32_bf16 v[40:43], v[136:139], v[96:99], v[40:43]
	v_mfma_f32_16x16x32_bf16 v[44:47], v[140:143], v[96:99], v[44:47]
	ds_read_b64 v[128:129], v229 offset:64
	ds_read_b64 v[130:131], v229 offset:96
	ds_read_b64 v[132:133], v229 offset:2368
	ds_read_b64 v[134:135], v229 offset:2400
	ds_read_b64 v[136:137], v229 offset:4672
	ds_read_b64 v[138:139], v229 offset:4704
	ds_read_b64 v[140:141], v229 offset:6976
	ds_read_b64 v[142:143], v229 offset:7008
	v_mfma_f32_16x16x32_bf16 v[48:51], v[144:147], v[96:99], v[48:51]
	v_mfma_f32_16x16x32_bf16 v[52:55], v[148:151], v[96:99], v[52:55]
	v_mfma_f32_16x16x32_bf16 v[56:59], v[152:155], v[96:99], v[56:59]
	v_mfma_f32_16x16x32_bf16 v[60:63], v[156:159], v[96:99], v[60:63]
	ds_read_b64 v[144:145], v229 offset:9280
	ds_read_b64 v[146:147], v229 offset:9312
	ds_read_b64 v[148:149], v229 offset:11584
	ds_read_b64 v[150:151], v229 offset:11616
	ds_read_b64 v[152:153], v229 offset:13888
	ds_read_b64 v[154:155], v229 offset:13920
	ds_read_b64 v[156:157], v229 offset:16192
	ds_read_b64 v[158:159], v229 offset:16224
	s_waitcnt lgkmcnt(8)
; __device__ __forceinline__ void phase_na(const Params& p, unsigned char* lds) {
;     ...
;             const bool band = kt >= 4; const int kr = rs_lo + kt - 4;
;             if (!(band && (kr < rsq || kr >= rsq + 8))) {
;                 const bf16_t* Kt = KtB + (kt & 1) * (64 * 136); const bf16_t* vt = vtB + (kt & 1) * (128 * 72);
;                 f32x4 st[2][4];
;                 const int wlo0 = min(max(qc0 - 8, 0), 48), whi0 = min(max(qc0 + 7, 0), 48) + 16, wlo1 = min(max(qc0 + 8, 0), 48), whi1 = min(max(qc0 + 23, 0), 48) + 16;
; #pragma unroll
;                 for (int nt = 0; nt < 4; ++nt) {
;                     const bool act0 = !band || (16 * nt < whi0 && 16 * nt + 16 > wlo0), act1 = !band || (16 * nt < whi1 && 16 * nt + 16 > wlo1);
;                     st[0][nt] = (f32x4){0.f, 0.f, 0.f, 0.f}; st[1][nt] = (f32x4){0.f, 0.f, 0.f, 0.f};
;                     if (act0 || act1) {
;                         bf16x8 Bk[4];
; #pragma unroll
;                         for (int ks = 0; ks < 4; ++ks) Bk[ks] = *(const bf16x8*)(Kt + (nt * 16 + fr) * 136 + ks * 32 + fq * 8);
; #pragma unroll
;     ...
; #pragma unroll
;                 for (int kk = 0; kk < 2; ++kk) {
;                     const int ta = 2 * kk, tb = 2 * kk + 1;
;                     const bf16x8 Bp0 = as_bf16x8((u32x4){pk[0][ta][0], pk[0][ta][1], pk[0][tb][0], pk[0][tb][1]}), Bp1 = as_bf16x8((u32x4){pk[1][ta][0], pk[1][ta][1], pk[1][tb][0], pk[1][tb][1]});
; #pragma unroll
;                     for (int dt = 0; dt < 8; ++dt) {
;                         const u32x2 va = *(const u32x2*)(vt + (dt * 16 + fr) * 72 + 16 * ta + fq * 4), vb = *(const u32x2*)(vt + (dt * 16 + fr) * 72 + 16 * tb + fq * 4);
;                         const bf16x8 Av = as_bf16x8((u32x4){va.x, va.y, vb.x, vb.y});
;                         Oa[0][dt] = __builtin_amdgcn_mfma_f32_16x16x32_bf16(Av, Bp0, Oa[0][dt], 0, 0, 0);
;                         Oa[1][dt] = __builtin_amdgcn_mfma_f32_16x16x32_bf16(Av, Bp1, Oa[1][dt], 0, 0, 0); }
;                     __builtin_amdgcn_sched_group_barrier(0x100, 8, 0);
; #pragma unroll
;                     for (int q = 0; q < 4; ++q) { __builtin_amdgcn_sched_group_barrier(0x008, 2, 0); __builtin_amdgcn_sched_group_barrier(0x100, 2, 0); }
;                     __builtin_amdgcn_sched_group_barrier(0x008, 8, 0);
;                     __builtin_amdgcn_sched_barrier(0);
;                 }
	v_mfma_f32_16x16x32_bf16 v[32:35], v[128:131], v[104:107], v[32:35]
	v_mfma_f32_16x16x32_bf16 v[64:67], v[128:131], v[120:123], v[64:67]
	v_mfma_f32_16x16x32_bf16 v[36:39], v[132:135], v[104:107], v[36:39]
	v_mfma_f32_16x16x32_bf16 v[68:71], v[132:135], v[120:123], v[68:71]
	v_mfma_f32_16x16x32_bf16 v[40:43], v[136:139], v[104:107], v[40:43]
	v_mfma_f32_16x16x32_bf16 v[72:75], v[136:139], v[120:123], v[72:75]
	v_mfma_f32_16x16x32_bf16 v[44:47], v[140:143], v[104:107], v[44:47]
	v_mfma_f32_16x16x32_bf16 v[76:79], v[140:143], v[120:123], v[76:79]
	s_waitcnt lgkmcnt(0)
	v_mfma_f32_16x16x32_bf16 v[48:51], v[144:147], v[104:107], v[48:51]
	v_mfma_f32_16x16x32_bf16 v[80:83], v[144:147], v[120:123], v[80:83]
	v_mfma_f32_16x16x32_bf16 v[52:55], v[148:151], v[104:107], v[52:55]
	v_mfma_f32_16x16x32_bf16 v[84:87], v[148:151], v[120:123], v[84:87]
	v_mfma_f32_16x16x32_bf16 v[56:59], v[152:155], v[104:107], v[56:59]
	v_mfma_f32_16x16x32_bf16 v[88:91], v[152:155], v[120:123], v[88:91]
	v_mfma_f32_16x16x32_bf16 v[60:63], v[156:159], v[104:107], v[60:63]
	v_mfma_f32_16x16x32_bf16 v[92:95], v[156:159], v[120:123], v[92:95]
	s_branch .Lna_tile_end
.Lna_c_ctx:
	ds_read_b128 v[128:131], v228 offset:0
	ds_read_b128 v[132:135], v228 offset:64
	ds_read_b128 v[136:139], v228 offset:128
	ds_read_b128 v[140:143], v228 offset:192
	v_mov_b32_e32 v96, 0
	v_mov_b32_e32 v97, 0
	v_mov_b32_e32 v98, 0
	v_mov_b32_e32 v99, 0
	v_mov_b32_e32 v100, 0
	v_mov_b32_e32 v101, 0
	v_mov_b32_e32 v102, 0
	v_mov_b32_e32 v103, 0
	v_mov_b32_e32 v104, 0
	v_mov_b32_e32 v105, 0
	v_mov_b32_e32 v106, 0
	v_mov_b32_e32 v107, 0
	v_mov_b32_e32 v108, 0
	v_mov_b32_e32 v109, 0
	v_mov_b32_e32 v110, 0
	v_mov_b32_e32 v111, 0
	v_mov_b32_e32 v112, 0
	v_mov_b32_e32 v113, 0
	v_mov_b32_e32 v114, 0
	v_mov_b32_e32 v115, 0
	v_mov_b32_e32 v116, 0
	v_mov_b32_e32 v117, 0
	v_mov_b32_e32 v118, 0
	v_mov_b32_e32 v119, 0
	v_mov_b32_e32 v120, 0
	v_mov_b32_e32 v121, 0
	v_mov_b32_e32 v122, 0
	v_mov_b32_e32 v123, 0
	v_mov_b32_e32 v124, 0
	v_mov_b32_e32 v125, 0
	v_mov_b32_e32 v126, 0
	v_mov_b32_e32 v127, 0
	ds_read_b128 v[144:147], v228 offset:4352
	ds_read_b128 v[148:151], v228 offset:4416
	ds_read_b128 v[152:155], v228 offset:4480
	ds_read_b128 v[156:159], v228 offset:4544
	s_waitcnt lgkmcnt(4)
	v_mfma_f32_16x16x32_bf16 v[96:99], v[128:131], v[0:3], v[96:99]
	v_mfma_f32_16x16x32_bf16 v[112:115], v[128:131], v[16:19], v[112:115]
	v_mfma_f32_16x16x32_bf16 v[96:99], v[132:135], v[4:7], v[96:99]
	v_mfma_f32_16x16x32_bf16 v[112:115], v[132:135], v[20:23], v[112:115]
	v_mfma_f32_16x16x32_bf16 v[96:99], v[136:139], v[8:11], v[96:99]
	v_mfma_f32_16x16x32_bf16 v[112:115], v[136:139], v[24:27], v[112:115]
	v_mfma_f32_16x16x32_bf16 v[96:99], v[140:143], v[12:15], v[96:99]
	v_mfma_f32_16x16x32_bf16 v[112:115], v[140:143], v[28:31], v[112:115]
	ds_read_b128 v[128:131], v228 offset:8704
	ds_read_b128 v[132:135], v228 offset:8768
	ds_read_b128 v[136:139], v228 offset:8832
	ds_read_b128 v[140:143], v228 offset:8896
	s_waitcnt lgkmcnt(4)
	v_mfma_f32_16x16x32_bf16 v[100:103], v[144:147], v[0:3], v[100:103]
	v_mfma_f32_16x16x32_bf16 v[116:119], v[144:147], v[16:19], v[116:119]
	v_mfma_f32_16x16x32_bf16 v[100:103], v[148:151], v[4:7], v[100:103]
	v_mfma_f32_16x16x32_bf16 v[116:119], v[148:151], v[20:23], v[116:119]
	v_mfma_f32_16x16x32_bf16 v[100:103], v[152:155], v[8:11], v[100:103]
	v_mfma_f32_16x16x32_bf16 v[116:119], v[152:155], v[24:27], v[116:119]
	v_mfma_f32_16x16x32_bf16 v[100:103], v[156:159], v[12:15], v[100:103]
	v_mfma_f32_16x16x32_bf16 v[116:119], v[156:159], v[28:31], v[116:119]
	ds_read_b128 v[144:147], v228 offset:13056
	ds_read_b128 v[148:151], v228 offset:13120
	ds_read_b128 v[152:155], v228 offset:13184
	ds_read_b128 v[156:159], v228 offset:13248
	s_waitcnt lgkmcnt(4)
	v_mfma_f32_16x16x32_bf16 v[104:107], v[128:131], v[0:3], v[104:107]
	v_mfma_f32_16x16x32_bf16 v[120:123], v[128:131], v[16:19], v[120:123]
	v_mfma_f32_16x16x32_bf16 v[104:107], v[132:135], v[4:7], v[104:107]
	v_mfma_f32_16x16x32_bf16 v[120:123], v[132:135], v[20:23], v[120:123]
	v_mfma_f32_16x16x32_bf16 v[104:107], v[136:139], v[8:11], v[104:107]
	v_mfma_f32_16x16x32_bf16 v[120:123], v[136:139], v[24:27], v[120:123]
	v_mfma_f32_16x16x32_bf16 v[104:107], v[140:143], v[12:15], v[104:107]
	v_mfma_f32_16x16x32_bf16 v[120:123], v[140:143], v[28:31], v[120:123]
	s_waitcnt lgkmcnt(0)
	v_mfma_f32_16x16x32_bf16 v[108:111], v[144:147], v[0:3], v[108:111]
	v_mfma_f32_16x16x32_bf16 v[124:127], v[144:147], v[16:19], v[124:127]
	v_mfma_f32_16x16x32_bf16 v[108:111], v[148:151], v[4:7], v[108:111]
	v_mfma_f32_16x16x32_bf16 v[124:127], v[148:151], v[20:23], v[124:127]
	v_mfma_f32_16x16x32_bf16 v[108:111], v[152:155], v[8:11], v[108:111]
	v_mfma_f32_16x16x32_bf16 v[124:127], v[152:155], v[24:27], v[124:127]
	v_mfma_f32_16x16x32_bf16 v[108:111], v[156:159], v[12:15], v[108:111]
	v_mfma_f32_16x16x32_bf16 v[124:127], v[156:159], v[28:31], v[124:127]
	ds_read_b64 v[128:129], v229 offset:0
	ds_read_b64 v[130:131], v229 offset:32
	ds_read_b64 v[132:133], v229 offset:2304
	ds_read_b64 v[134:135], v229 offset:2336
	ds_read_b64 v[136:137], v229 offset:4608
	ds_read_b64 v[138:139], v229 offset:4640
	ds_read_b64 v[140:141], v229 offset:6912
	ds_read_b64 v[142:143], v229 offset:6944
	ds_read_b64 v[144:145], v229 offset:9216
	ds_read_b64 v[146:147], v229 offset:9248
	ds_read_b64 v[148:149], v229 offset:11520
	ds_read_b64 v[150:151], v229 offset:11552
	ds_read_b64 v[152:153], v229 offset:13824
	ds_read_b64 v[154:155], v229 offset:13856
	ds_read_b64 v[156:157], v229 offset:16128
	ds_read_b64 v[158:159], v229 offset:16160
	v_max3_f32 v232, v96, v97, v98
	v_max3_f32 v234, v99, v100, v101
	v_max3_f32 v236, v102, v103, v104
	v_max3_f32 v232, v232, v105, v106
	v_max_f32_e32 v232, v232, v107
	v_max3_f32 v234, v234, v108, v109
	v_max_f32_e32 v234, v234, v110
	v_max_f32_e32 v236, v236, v111
	v_max3_f32 v232, v232, v234, v236
	v_max3_f32 v233, v112, v113, v114
	v_max3_f32 v235, v115, v116, v117
	v_max3_f32 v237, v118, v119, v120
	v_max3_f32 v233, v233, v121, v122
	v_max_f32_e32 v233, v233, v123
	v_max3_f32 v235, v235, v124, v125
	v_max_f32_e32 v235, v235, v126
	v_max_f32_e32 v237, v237, v127
	v_max3_f32 v233, v233, v235, v237
	v_mul_f32_e32 v232, s30, v232
	v_mul_f32_e32 v233, s30, v233
	v_sub_f32_e32 v236, v232, v222
	v_sub_f32_e32 v237, v233, v223
	v_max_f32_e32 v236, v236, v237
	v_cmp_lt_f32_e32 vcc, 0x41000000, v236
	s_cbranch_vccz .Lna_fast_ctx
; __device__ __forceinline__ unsigned pk2(float lo, float hi) { return __builtin_bit_cast(unsigned, __builtin_convertvector((f32x2){lo, hi}, hwbf16x2)); }
; __device__ __forceinline__ void phase_na(const Params& p, unsigned char* lds) {
;     ...
;                     mx = fmaxf(mx, __shfl_xor(mx, 16)); mx = fmaxf(mx, __shfl_xor(mx, 32));
;                     const bool resc = !__all(mx - mrow[mt] <= 8.0f);
;                     float mn = mrow[mt], alpha = 1.f;
;                     if (resc) { mn = fmaxf(mrow[mt], mx); alpha = __builtin_amdgcn_exp2f(mrow[mt] - mn); mrow[mt] = mn; }
;                     float ls = 0.f;
; #pragma unroll
;                     for (int nt = 0; nt < 4; ++nt) {
;                         const bool act = !band || (16 * nt < whi && 16 * nt + 16 > wlo);
;                         if (act) { const float p0 = __builtin_amdgcn_exp2f(st[mt][nt][0] - mn), p1 = __builtin_amdgcn_exp2f(st[mt][nt][1] - mn), p2 = __builtin_amdgcn_exp2f(st[mt][nt][2] - mn), p3 = __builtin_amdgcn_exp2f(st[mt][nt][3] - mn);
;                             ls += (p0 + p1) + (p2 + p3); pk[mt][nt][0] = pk2(p0, p1); pk[mt][nt][1] = pk2(p2, p3); }
;                         else { pk[mt][nt][0] = 0u; pk[mt][nt][1] = 0u; }
;                     }
;                     lrow[mt] = lrow[mt] * alpha + ls;
;                     if (resc) {
; #pragma unroll
;                         for (int dt = 0; dt < 8; ++dt) Oa[mt][dt] = Oa[mt][dt] * alpha; }
	ds_bpermute_b32 v234, v218, v232
	ds_bpermute_b32 v235, v218, v233
	s_waitcnt lgkmcnt(0)
	v_max_f32_e32 v232, v232, v234
	v_max_f32_e32 v233, v233, v235
	ds_bpermute_b32 v234, v219, v232
	ds_bpermute_b32 v235, v219, v233
	s_waitcnt lgkmcnt(0)
	v_max_f32_e32 v232, v232, v234
	v_max_f32_e32 v233, v233, v235
	v_max_f32_e32 v236, v222, v232
	v_sub_f32_e32 v237, v222, v236
	v_exp_f32_e32 v237, v237
	v_mov_b32_e32 v222, v236
	v_sub_f32_e32 v226, 0, v236
	v_mul_f32_e32 v224, v224, v237
	v_mul_f32_e32 v32, v32, v237
	v_mul_f32_e32 v33, v33, v237
	v_mul_f32_e32 v34, v34, v237
	v_mul_f32_e32 v35, v35, v237
	v_mul_f32_e32 v36, v36, v237
	v_mul_f32_e32 v37, v37, v237
	v_mul_f32_e32 v38, v38, v237
	v_mul_f32_e32 v39, v39, v237
	v_mul_f32_e32 v40, v40, v237
	v_mul_f32_e32 v41, v41, v237
	v_mul_f32_e32 v42, v42, v237
	v_mul_f32_e32 v43, v43, v237
	v_mul_f32_e32 v44, v44, v237
	v_mul_f32_e32 v45, v45, v237
	v_mul_f32_e32 v46, v46, v237
	v_mul_f32_e32 v47, v47, v237
	v_mul_f32_e32 v48, v48, v237
	v_mul_f32_e32 v49, v49, v237
	v_mul_f32_e32 v50, v50, v237
	v_mul_f32_e32 v51, v51, v237
	v_mul_f32_e32 v52, v52, v237
	v_mul_f32_e32 v53, v53, v237
	v_mul_f32_e32 v54, v54, v237
	v_mul_f32_e32 v55, v55, v237
	v_mul_f32_e32 v56, v56, v237
	v_mul_f32_e32 v57, v57, v237
	v_mul_f32_e32 v58, v58, v237
	v_mul_f32_e32 v59, v59, v237
	v_mul_f32_e32 v60, v60, v237
	v_mul_f32_e32 v61, v61, v237
	v_mul_f32_e32 v62, v62, v237
	v_mul_f32_e32 v63, v63, v237
	v_max_f32_e32 v236, v223, v233
	v_sub_f32_e32 v237, v223, v236
	v_exp_f32_e32 v237, v237
	v_mov_b32_e32 v223, v236
	v_sub_f32_e32 v227, 0, v236
	v_mul_f32_e32 v225, v225, v237
	v_mul_f32_e32 v64, v64, v237
	v_mul_f32_e32 v65, v65, v237
	v_mul_f32_e32 v66, v66, v237
	v_mul_f32_e32 v67, v67, v237
	v_mul_f32_e32 v68, v68, v237
	v_mul_f32_e32 v69, v69, v237
	v_mul_f32_e32 v70, v70, v237
	v_mul_f32_e32 v71, v71, v237
	v_mul_f32_e32 v72, v72, v237
	v_mul_f32_e32 v73, v73, v237
	v_mul_f32_e32 v74, v74, v237
	v_mul_f32_e32 v75, v75, v237
	v_mul_f32_e32 v76, v76, v237
	v_mul_f32_e32 v77, v77, v237
	v_mul_f32_e32 v78, v78, v237
	v_mul_f32_e32 v79, v79, v237
	v_mul_f32_e32 v80, v80, v237
	v_mul_f32_e32 v81, v81, v237
	v_mul_f32_e32 v82, v82, v237
	v_mul_f32_e32 v83, v83, v237
	v_mul_f32_e32 v84, v84, v237
	v_mul_f32_e32 v85, v85, v237
	v_mul_f32_e32 v86, v86, v237
	v_mul_f32_e32 v87, v87, v237
	v_mul_f32_e32 v88, v88, v237
	v_mul_f32_e32 v89, v89, v237
	v_mul_f32_e32 v90, v90, v237
	v_mul_f32_e32 v91, v91, v237
	v_mul_f32_e32 v92, v92, v237
	v_mul_f32_e32 v93, v93, v237
	v_mul_f32_e32 v94, v94, v237
	v_mul_f32_e32 v95, v95, v237
.Lna_fast_ctx:
	v_fma_f32 v96, v96, s30, v226
	v_fma_f32 v97, v97, s30, v226
	v_fma_f32 v98, v98, s30, v226
	v_fma_f32 v99, v99, s30, v226
	v_fma_f32 v100, v100, s30, v226
	v_fma_f32 v101, v101, s30, v226
	v_fma_f32 v102, v102, s30, v226
	v_fma_f32 v103, v103, s30, v226
	v_fma_f32 v104, v104, s30, v226
	v_fma_f32 v105, v105, s30, v226
	v_fma_f32 v106, v106, s30, v226
	v_fma_f32 v107, v107, s30, v226
	v_fma_f32 v108, v108, s30, v226
	v_fma_f32 v109, v109, s30, v226
	v_fma_f32 v110, v110, s30, v226
	v_fma_f32 v111, v111, s30, v226
	v_fma_f32 v112, v112, s30, v227
	v_fma_f32 v113, v113, s30, v227
	v_fma_f32 v114, v114, s30, v227
	v_fma_f32 v115, v115, s30, v227
	v_fma_f32 v116, v116, s30, v227
	v_fma_f32 v117, v117, s30, v227
	v_fma_f32 v118, v118, s30, v227
	v_fma_f32 v119, v119, s30, v227
	v_fma_f32 v120, v120, s30, v227
	v_fma_f32 v121, v121, s30, v227
	v_fma_f32 v122, v122, s30, v227
	v_fma_f32 v123, v123, s30, v227
	v_fma_f32 v124, v124, s30, v227
	v_fma_f32 v125, v125, s30, v227
	v_fma_f32 v126, v126, s30, v227
	v_fma_f32 v127, v127, s30, v227
	v_exp_f32_e32 v96, v96
	v_exp_f32_e32 v97, v97
	v_exp_f32_e32 v98, v98
	v_exp_f32_e32 v99, v99
	v_exp_f32_e32 v100, v100
	v_exp_f32_e32 v101, v101
	v_exp_f32_e32 v102, v102
	v_exp_f32_e32 v103, v103
	v_exp_f32_e32 v104, v104
	v_exp_f32_e32 v105, v105
	v_exp_f32_e32 v106, v106
	v_exp_f32_e32 v107, v107
	v_exp_f32_e32 v108, v108
	v_exp_f32_e32 v109, v109
	v_exp_f32_e32 v110, v110
	v_exp_f32_e32 v111, v111
	v_exp_f32_e32 v112, v112
	v_exp_f32_e32 v113, v113
	v_exp_f32_e32 v114, v114
	v_exp_f32_e32 v115, v115
	v_exp_f32_e32 v116, v116
	v_exp_f32_e32 v117, v117
	v_exp_f32_e32 v118, v118
	v_exp_f32_e32 v119, v119
	v_exp_f32_e32 v120, v120
	v_exp_f32_e32 v121, v121
	v_exp_f32_e32 v122, v122
	v_exp_f32_e32 v123, v123
	v_exp_f32_e32 v124, v124
	v_exp_f32_e32 v125, v125
	v_exp_f32_e32 v126, v126
	v_exp_f32_e32 v127, v127
	v_add_f32_e32 v232, v96, v97
	v_add_f32_e32 v232, v232, v98
	v_add_f32_e32 v232, v232, v99
	v_add_f32_e32 v232, v232, v100
	v_add_f32_e32 v232, v232, v101
	v_add_f32_e32 v232, v232, v102
	v_add_f32_e32 v232, v232, v103
	v_add_f32_e32 v232, v232, v104
	v_add_f32_e32 v232, v232, v105
	v_add_f32_e32 v232, v232, v106
	v_add_f32_e32 v232, v232, v107
	v_add_f32_e32 v232, v232, v108
	v_add_f32_e32 v232, v232, v109
	v_add_f32_e32 v232, v232, v110
	v_add_f32_e32 v232, v232, v111
	v_add_f32_e32 v224, v224, v232
	v_add_f32_e32 v233, v112, v113
	v_add_f32_e32 v233, v233, v114
	v_add_f32_e32 v233, v233, v115
	v_add_f32_e32 v233, v233, v116
	v_add_f32_e32 v233, v233, v117
	v_add_f32_e32 v233, v233, v118
	v_add_f32_e32 v233, v233, v119
	v_add_f32_e32 v233, v233, v120
	v_add_f32_e32 v233, v233, v121
	v_add_f32_e32 v233, v233, v122
	v_add_f32_e32 v233, v233, v123
	v_add_f32_e32 v233, v233, v124
	v_add_f32_e32 v233, v233, v125
	v_add_f32_e32 v233, v233, v126
	v_add_f32_e32 v233, v233, v127
	v_add_f32_e32 v225, v225, v233
	v_cvt_pk_bf16_f32 v96, v96, v97
	v_cvt_pk_bf16_f32 v97, v98, v99
	v_cvt_pk_bf16_f32 v98, v100, v101
	v_cvt_pk_bf16_f32 v99, v102, v103
	v_cvt_pk_bf16_f32 v104, v104, v105
	v_cvt_pk_bf16_f32 v105, v106, v107
	v_cvt_pk_bf16_f32 v106, v108, v109
	v_cvt_pk_bf16_f32 v107, v110, v111
	v_cvt_pk_bf16_f32 v112, v112, v113
	v_cvt_pk_bf16_f32 v113, v114, v115
	v_cvt_pk_bf16_f32 v114, v116, v117
	v_cvt_pk_bf16_f32 v115, v118, v119
	v_cvt_pk_bf16_f32 v120, v120, v121
	v_cvt_pk_bf16_f32 v121, v122, v123
	v_cvt_pk_bf16_f32 v122, v124, v125
	v_cvt_pk_bf16_f32 v123, v126, v127
	s_waitcnt lgkmcnt(0)
; __device__ __forceinline__ void phase_na(const Params& p, unsigned char* lds) {
;     ...
; #pragma unroll
;                 for (int kk = 0; kk < 2; ++kk) {
;                     const int ta = 2 * kk, tb = 2 * kk + 1;
;                     const bf16x8 Bp0 = as_bf16x8((u32x4){pk[0][ta][0], pk[0][ta][1], pk[0][tb][0], pk[0][tb][1]}), Bp1 = as_bf16x8((u32x4){pk[1][ta][0], pk[1][ta][1], pk[1][tb][0], pk[1][tb][1]});
; #pragma unroll
;                     for (int dt = 0; dt < 8; ++dt) {
;                         const u32x2 va = *(const u32x2*)(vt + (dt * 16 + fr) * 72 + 16 * ta + fq * 4), vb = *(const u32x2*)(vt + (dt * 16 + fr) * 72 + 16 * tb + fq * 4);
;                         const bf16x8 Av = as_bf16x8((u32x4){va.x, va.y, vb.x, vb.y});
;                         Oa[0][dt] = __builtin_amdgcn_mfma_f32_16x16x32_bf16(Av, Bp0, Oa[0][dt], 0, 0, 0);
;                         Oa[1][dt] = __builtin_amdgcn_mfma_f32_16x16x32_bf16(Av, Bp1, Oa[1][dt], 0, 0, 0); }
;                     __builtin_amdgcn_sched_group_barrier(0x100, 8, 0);
; #pragma unroll
;                     for (int q = 0; q < 4; ++q) { __builtin_amdgcn_sched_group_barrier(0x008, 2, 0); __builtin_amdgcn_sched_group_barrier(0x100, 2, 0); }
;                     __builtin_amdgcn_sched_group_barrier(0x008, 8, 0);
;                     __builtin_amdgcn_sched_barrier(0);
;                 }
	s_nop 1
	v_mfma_f32_16x16x32_bf16 v[32:35], v[128:131], v[96:99], v[32:35]
	v_mfma_f32_16x16x32_bf16 v[64:67], v[128:131], v[112:115], v[64:67]
	v_mfma_f32_16x16x32_bf16 v[36:39], v[132:135], v[96:99], v[36:39]
	v_mfma_f32_16x16x32_bf16 v[68:71], v[132:135], v[112:115], v[68:71]
	v_mfma_f32_16x16x32_bf16 v[40:43], v[136:139], v[96:99], v[40:43]
	v_mfma_f32_16x16x32_bf16 v[72:75], v[136:139], v[112:115], v[72:75]
	v_mfma_f32_16x16x32_bf16 v[44:47], v[140:143], v[96:99], v[44:47]
	v_mfma_f32_16x16x32_bf16 v[76:79], v[140:143], v[112:115], v[76:79]
	ds_read_b64 v[128:129], v229 offset:64
	ds_read_b64 v[130:131], v229 offset:96
	ds_read_b64 v[132:133], v229 offset:2368
	ds_read_b64 v[134:135], v229 offset:2400
	ds_read_b64 v[136:137], v229 offset:4672
	ds_read_b64 v[138:139], v229 offset:4704
	ds_read_b64 v[140:141], v229 offset:6976
	ds_read_b64 v[142:143], v229 offset:7008
	v_mfma_f32_16x16x32_bf16 v[48:51], v[144:147], v[96:99], v[48:51]
	v_mfma_f32_16x16x32_bf16 v[80:83], v[144:147], v[112:115], v[80:83]
	v_mfma_f32_16x16x32_bf16 v[52:55], v[148:151], v[96:99], v[52:55]
	v_mfma_f32_16x16x32_bf16 v[84:87], v[148:151], v[112:115], v[84:87]
	v_mfma_f32_16x16x32_bf16 v[56:59], v[152:155], v[96:99], v[56:59]
	v_mfma_f32_16x16x32_bf16 v[88:91], v[152:155], v[112:115], v[88:91]
	v_mfma_f32_16x16x32_bf16 v[60:63], v[156:159], v[96:99], v[60:63]
	v_mfma_f32_16x16x32_bf16 v[92:95], v[156:159], v[112:115], v[92:95]
	ds_read_b64 v[144:145], v229 offset:9280
	ds_read_b64 v[146:147], v229 offset:9312
	ds_read_b64 v[148:149], v229 offset:11584
	ds_read_b64 v[150:151], v229 offset:11616
	ds_read_b64 v[152:153], v229 offset:13888
	ds_read_b64 v[154:155], v229 offset:13920
	ds_read_b64 v[156:157], v229 offset:16192
	ds_read_b64 v[158:159], v229 offset:16224
	s_waitcnt lgkmcnt(8)
	v_mfma_f32_16x16x32_bf16 v[32:35], v[128:131], v[104:107], v[32:35]
	v_mfma_f32_16x16x32_bf16 v[64:67], v[128:131], v[120:123], v[64:67]
	v_mfma_f32_16x16x32_bf16 v[36:39], v[132:135], v[104:107], v[36:39]
	v_mfma_f32_16x16x32_bf16 v[68:71], v[132:135], v[120:123], v[68:71]
	v_mfma_f32_16x16x32_bf16 v[40:43], v[136:139], v[104:107], v[40:43]
	v_mfma_f32_16x16x32_bf16 v[72:75], v[136:139], v[120:123], v[72:75]
	v_mfma_f32_16x16x32_bf16 v[44:47], v[140:143], v[104:107], v[44:47]
	v_mfma_f32_16x16x32_bf16 v[76:79], v[140:143], v[120:123], v[76:79]
	s_waitcnt lgkmcnt(0)
	v_mfma_f32_16x16x32_bf16 v[48:51], v[144:147], v[104:107], v[48:51]
	v_mfma_f32_16x16x32_bf16 v[80:83], v[144:147], v[120:123], v[80:83]
	v_mfma_f32_16x16x32_bf16 v[52:55], v[148:151], v[104:107], v[52:55]
	v_mfma_f32_16x16x32_bf16 v[84:87], v[148:151], v[120:123], v[84:87]
	v_mfma_f32_16x16x32_bf16 v[56:59], v[152:155], v[104:107], v[56:59]
	v_mfma_f32_16x16x32_bf16 v[88:91], v[152:155], v[120:123], v[88:91]
	v_mfma_f32_16x16x32_bf16 v[60:63], v[156:159], v[104:107], v[60:63]
	v_mfma_f32_16x16x32_bf16 v[92:95], v[156:159], v[120:123], v[92:95]
	s_branch .Lna_tile_end
; __device__ __forceinline__ unsigned pk2(float lo, float hi) { return __builtin_bit_cast(unsigned, __builtin_convertvector((f32x2){lo, hi}, hwbf16x2)); }
; __device__ __forceinline__ void phase_na(const Params& p, unsigned char* lds) {
;     ...
;             __syncthreads();
;         }
;         { bf16_t* ost = KtB + w * (32 * 136);
; #pragma unroll
;           for (int mt = 0; mt < 2; ++mt) {
;             float l = lrow[mt]; l += __shfl_xor(l, 16); l += __shfl_xor(l, 32); const float inv = 1.f / l;
; #pragma unroll
;             for (int dt = 0; dt < 8; ++dt) *(u32x2*)(ost + (mt * 16 + fr) * 136 + dt * 16 + fq * 4) = (u32x2){pk2(Oa[mt][dt][0] * inv, Oa[mt][dt][1] * inv), pk2(Oa[mt][dt][2] * inv, Oa[mt][dt][3] * inv)}; }
;           asm volatile("s_waitcnt lgkmcnt(0)" ::: "memory");
;           const int q = lane >> 1, hf = lane & 1;
;           bf16_t* op = O + (size_t)(b * SEQ + qr * 64 + qc0 + q) * D + h * 128 + hf * 64;
; #pragma unroll
;           for (int e = 0; e < 8; ++e) *(u32x4*)(op + e * 8) = *(const u32x4*)(ost + q * 136 + hf * 64 + e * 8); }
.Lna_tile_end:
	s_waitcnt lgkmcnt(0)
	s_barrier
	s_mov_b32 s65, s66
	s_add_i32 s66, s66, 1
	s_cmp_eq_u32 s66, 3
	s_cselect_b32 s66, 0, s66
	s_add_i32 s21, s21, 1
	s_cmp_lt_u32 s21, s18
	s_cbranch_scc1 .Lna_tile
	ds_bpermute_b32 v232, v218, v224
	ds_bpermute_b32 v233, v218, v225
	s_waitcnt lgkmcnt(0)
	v_add_f32_e32 v232, v232, v224
	v_add_f32_e32 v233, v233, v225
	ds_bpermute_b32 v234, v219, v232
	ds_bpermute_b32 v235, v219, v233
	s_waitcnt lgkmcnt(0)
	v_add_f32_e32 v232, v232, v234
	v_add_f32_e32 v233, v233, v235
	v_rcp_f32_e32 v234, v232
	s_nop 0
	v_fma_f32 v236, -v232, v234, 1.0
	v_fma_f32 v234, v236, v234, v234
	v_rcp_f32_e32 v235, v233
	s_nop 0
	v_fma_f32 v237, -v233, v235, 1.0
	v_fma_f32 v235, v237, v235, v235
	s_mul_i32 s0, s10, 0x2200
	v_and_b32_e32 v238, 15, v162
	v_mul_u32_u24_e32 v238, 0x110, v238
	v_bfe_u32 v239, v162, 4, 2
	v_lshl_add_u32 v238, v239, 3, v238
	v_add_u32_e32 v238, s0, v238
	v_mul_f32_e32 v32, v32, v234
	v_mul_f32_e32 v33, v33, v234
	v_mul_f32_e32 v34, v34, v234
	v_mul_f32_e32 v35, v35, v234
	v_cvt_pk_bf16_f32 v32, v32, v33
	v_cvt_pk_bf16_f32 v33, v34, v35
	ds_write_b64 v238, v[32:33] offset:0
	v_mul_f32_e32 v36, v36, v234
	v_mul_f32_e32 v37, v37, v234
	v_mul_f32_e32 v38, v38, v234
	v_mul_f32_e32 v39, v39, v234
	v_cvt_pk_bf16_f32 v36, v36, v37
	v_cvt_pk_bf16_f32 v37, v38, v39
	ds_write_b64 v238, v[36:37] offset:32
	v_mul_f32_e32 v40, v40, v234
	v_mul_f32_e32 v41, v41, v234
	v_mul_f32_e32 v42, v42, v234
	v_mul_f32_e32 v43, v43, v234
	v_cvt_pk_bf16_f32 v40, v40, v41
	v_cvt_pk_bf16_f32 v41, v42, v43
	ds_write_b64 v238, v[40:41] offset:64
	v_mul_f32_e32 v44, v44, v234
	v_mul_f32_e32 v45, v45, v234
	v_mul_f32_e32 v46, v46, v234
	v_mul_f32_e32 v47, v47, v234
	v_cvt_pk_bf16_f32 v44, v44, v45
	v_cvt_pk_bf16_f32 v45, v46, v47
	ds_write_b64 v238, v[44:45] offset:96
	v_mul_f32_e32 v48, v48, v234
	v_mul_f32_e32 v49, v49, v234
	v_mul_f32_e32 v50, v50, v234
	v_mul_f32_e32 v51, v51, v234
	v_cvt_pk_bf16_f32 v48, v48, v49
	v_cvt_pk_bf16_f32 v49, v50, v51
	ds_write_b64 v238, v[48:49] offset:128
	v_mul_f32_e32 v52, v52, v234
	v_mul_f32_e32 v53, v53, v234
	v_mul_f32_e32 v54, v54, v234
	v_mul_f32_e32 v55, v55, v234
	v_cvt_pk_bf16_f32 v52, v52, v53
	v_cvt_pk_bf16_f32 v53, v54, v55
	ds_write_b64 v238, v[52:53] offset:160
	v_mul_f32_e32 v56, v56, v234
	v_mul_f32_e32 v57, v57, v234
	v_mul_f32_e32 v58, v58, v234
	v_mul_f32_e32 v59, v59, v234
	v_cvt_pk_bf16_f32 v56, v56, v57
	v_cvt_pk_bf16_f32 v57, v58, v59
	ds_write_b64 v238, v[56:57] offset:192
	v_mul_f32_e32 v60, v60, v234
	v_mul_f32_e32 v61, v61, v234
	v_mul_f32_e32 v62, v62, v234
	v_mul_f32_e32 v63, v63, v234
	v_cvt_pk_bf16_f32 v60, v60, v61
	v_cvt_pk_bf16_f32 v61, v62, v63
	ds_write_b64 v238, v[60:61] offset:224
	v_mul_f32_e32 v64, v64, v235
	v_mul_f32_e32 v65, v65, v235
	v_mul_f32_e32 v66, v66, v235
	v_mul_f32_e32 v67, v67, v235
	v_cvt_pk_bf16_f32 v64, v64, v65
	v_cvt_pk_bf16_f32 v65, v66, v67
	ds_write_b64 v238, v[64:65] offset:4352
	v_mul_f32_e32 v68, v68, v235
	v_mul_f32_e32 v69, v69, v235
	v_mul_f32_e32 v70, v70, v235
	v_mul_f32_e32 v71, v71, v235
	v_cvt_pk_bf16_f32 v68, v68, v69
	v_cvt_pk_bf16_f32 v69, v70, v71
	ds_write_b64 v238, v[68:69] offset:4384
	v_mul_f32_e32 v72, v72, v235
	v_mul_f32_e32 v73, v73, v235
	v_mul_f32_e32 v74, v74, v235
	v_mul_f32_e32 v75, v75, v235
	v_cvt_pk_bf16_f32 v72, v72, v73
	v_cvt_pk_bf16_f32 v73, v74, v75
	ds_write_b64 v238, v[72:73] offset:4416
	v_mul_f32_e32 v76, v76, v235
	v_mul_f32_e32 v77, v77, v235
	v_mul_f32_e32 v78, v78, v235
	v_mul_f32_e32 v79, v79, v235
	v_cvt_pk_bf16_f32 v76, v76, v77
	v_cvt_pk_bf16_f32 v77, v78, v79
	ds_write_b64 v238, v[76:77] offset:4448
	v_mul_f32_e32 v80, v80, v235
	v_mul_f32_e32 v81, v81, v235
	v_mul_f32_e32 v82, v82, v235
	v_mul_f32_e32 v83, v83, v235
	v_cvt_pk_bf16_f32 v80, v80, v81
	v_cvt_pk_bf16_f32 v81, v82, v83
	ds_write_b64 v238, v[80:81] offset:4480
	v_mul_f32_e32 v84, v84, v235
	v_mul_f32_e32 v85, v85, v235
	v_mul_f32_e32 v86, v86, v235
	v_mul_f32_e32 v87, v87, v235
	v_cvt_pk_bf16_f32 v84, v84, v85
	v_cvt_pk_bf16_f32 v85, v86, v87
	ds_write_b64 v238, v[84:85] offset:4512
	v_mul_f32_e32 v88, v88, v235
	v_mul_f32_e32 v89, v89, v235
	v_mul_f32_e32 v90, v90, v235
	v_mul_f32_e32 v91, v91, v235
	v_cvt_pk_bf16_f32 v88, v88, v89
	v_cvt_pk_bf16_f32 v89, v90, v91
	ds_write_b64 v238, v[88:89] offset:4544
	v_mul_f32_e32 v92, v92, v235
	v_mul_f32_e32 v93, v93, v235
	v_mul_f32_e32 v94, v94, v235
	v_mul_f32_e32 v95, v95, v235
	v_cvt_pk_bf16_f32 v92, v92, v93
	v_cvt_pk_bf16_f32 v93, v94, v95
	ds_write_b64 v238, v[92:93] offset:4576
	s_waitcnt lgkmcnt(0)
	v_and_b32_e32 v232, 63, v162
	v_lshrrev_b32_e32 v233, 1, v232
	v_and_b32_e32 v234, 1, v232
	v_mul_u32_u24_e32 v235, 0x110, v233
	v_lshl_add_u32 v235, v234, 7, v235
	v_add_u32_e32 v235, s0, v235
	ds_read_b128 v[128:131], v235 offset:0
	ds_read_b128 v[132:135], v235 offset:16
	ds_read_b128 v[136:139], v235 offset:32
	ds_read_b128 v[140:143], v235 offset:48
	ds_read_b128 v[144:147], v235 offset:64
	ds_read_b128 v[148:151], v235 offset:80
	ds_read_b128 v[152:155], v235 offset:96
	ds_read_b128 v[156:159], v235 offset:112
	s_lshl_b32 s0, s15, 12
	s_lshl_b32 s1, s19, 6
	s_add_i32 s0, s0, s1
	s_add_i32 s0, s0, s12
	v_add_u32_e32 v233, s0, v233
	v_lshlrev_b32_e32 v233, 12, v233
	v_lshl_add_u32 v233, v234, 7, v233
	s_lshl_b32 s1, s14, 8
	v_add_u32_e32 v233, s1, v233
	s_waitcnt lgkmcnt(7)
	global_store_dwordx4 v233, v[128:131], s[8:9] offset:0
	s_waitcnt lgkmcnt(6)
	global_store_dwordx4 v233, v[132:135], s[8:9] offset:16
	s_waitcnt lgkmcnt(5)
	global_store_dwordx4 v233, v[136:139], s[8:9] offset:32
	s_waitcnt lgkmcnt(4)
	global_store_dwordx4 v233, v[140:143], s[8:9] offset:48
	s_waitcnt lgkmcnt(3)
	global_store_dwordx4 v233, v[144:147], s[8:9] offset:64
	s_waitcnt lgkmcnt(2)
	global_store_dwordx4 v233, v[148:151], s[8:9] offset:80
	s_waitcnt lgkmcnt(1)
	global_store_dwordx4 v233, v[152:155], s[8:9] offset:96
	s_waitcnt lgkmcnt(0)
	global_store_dwordx4 v233, v[156:159], s[8:9] offset:112
	s_add_i32 s13, s13, s82
	s_branch .Lna_unit
